# RG gate GEMM epilogue: the 64 per-element exec-masked if/else blocks (expm1 polynomial vs exp) replaced by computing both and one v_cndmask
# baseline (speedup 1.0000x reference)
; __device__ __forceinline__ unsigned cvt_pk_bf16(float lo, float hi) { const f32x2_t v = {lo, hi}; const bf16x2_t b = __builtin_convertvector(v, bf16x2_t); return __builtin_bit_cast(unsigned, b); }
; __device__ __forceinline__ float lo_bf(unsigned w) { return __uint_as_float(w << 16); }
; __device__ __forceinline__ float hi_bf(unsigned w) { return __uint_as_float(w & 0xffff0000u); }
; __device__ __forceinline__ float sigmoidf_(float x) { return __builtin_amdgcn_rcpf(1.0f + __builtin_amdgcn_exp2f(-1.4426950408889634f * x)); }
;     __device__ __forceinline__ void operator()(AccRef acc, const Unit& u, int wr, int wc, int fr, int fq) const {
;         const int row0 = u.pm * BM + wr * 64 + fr;
; #pragma unroll
;         for (int bj = 0; bj < 2; ++bj) { const int c = u.pn * BM + bj * HALF + wc * 32; const int dir = c >> 10; const int ch = ((c & 1023) >> 1) + 4 * fq;
;             const f32x4 vba = *(const f32x4*)(ba + dir * 512 + ch), vbx = *(const f32x4*)(bx + dir * 512 + ch), vl = *(const f32x4*)(lam + dir * 512 + ch);
;             const f32x4 cc = vl;
; #pragma unroll
;             for (int ai = 0; ai < 2; ++ai) {
;                 u32x2 xwv[4];
; #pragma unroll
;                 for (int m = 0; m < 4; ++m) xwv[m] = *(const u32x2*)(xc + (size_t)(row0 + ai * HALF + m * 16) * 512 + ch);
; #pragma unroll
;                 for (int m = 0; m < 4; ++m) { const size_t row = (size_t)(row0 + ai * HALF + m * 16);
;                     const u32x2 xw = xwv[m];
;                     const float xv[4] = {lo_bf(xw.x), hi_bf(xw.x), lo_bf(xw.y), hi_bf(xw.y)};
;                     float la[4], uo[4];
; #pragma unroll
;                     for (int i = 0; i < 4; ++i) { const float r = sigmoidf_(acc[ai][bj][m][0][i] + vba[i]), gi = sigmoidf_(acc[ai][bj][m][1][i] + vbx[i]);
;                         const float l = cc[i] * r; la[i] = l; const float x2 = 2.0f * l;
;                         const float em1 = (x2 > -0.25f) ? x2 * (1.0f + x2 * (0.5f + x2 * (1.0f / 6.0f + x2 * (1.0f / 24.0f + x2 * (1.0f / 120.0f + x2 * (1.0f / 720.0f)))))) : (__expf(x2) - 1.0f);
;                         uo[i] = __builtin_amdgcn_sqrtf(fmaxf(-em1, 0.0f)) * gi * xv[i]; }
;                     u32x2 w0, w1; w0.x = cvt_pk_bf16(la[0], la[1]); w0.y = cvt_pk_bf16(la[2], la[3]); w1.x = cvt_pk_bf16(uo[0], uo[1]); w1.y = cvt_pk_bf16(uo[2], uo[3]);
.LBB0_503:
	s_and_b64 vcc, exec, s[78:79]
	v_or_b32_e32 v144, 16, v218
	v_or_b32_e32 v142, 32, v218
	v_or_b32_e32 v140, 48, v218
	s_cbranch_vccz .LBB0_761
	s_and_b32 s6, s51, 0x300
	s_or_b32 s6, s6, s77
	s_ashr_i32 s22, s70, 2
	s_lshr_b32 s6, s6, 1
	v_or_b32_e32 v141, s6, v247
	s_lshl_b32 s6, s22, 9
	s_ashr_i32 s7, s6, 31
	s_lshl_b64 s[60:61], s[6:7], 2
	s_add_u32 s46, s72, s60
	s_addc_u32 s47, s73, s61
	v_lshlrev_b32_e32 v146, 2, v141
	s_add_u32 s6, s56, s60
	s_addc_u32 s7, s57, s61
	global_load_dwordx4 v[132:135], v146, s[46:47]
	s_waitcnt lgkmcnt(0)
	global_load_dwordx4 v[128:131], v146, s[6:7]
	v_lshlrev_b32_e32 v184, 1, v141
	v_ashrrev_i32_e32 v219, 31, v218
	v_lshl_add_u64 v[166:167], s[42:43], 0, v[184:185]
	v_lshlrev_b64 v[148:149], 10, v[218:219]
	v_ashrrev_i32_e32 v145, 31, v144
	s_add_u32 s78, s20, s60
	v_lshl_add_u64 v[150:151], v[166:167], 0, v[148:149]
	v_lshlrev_b64 v[148:149], 10, v[144:145]
	v_ashrrev_i32_e32 v143, 31, v142
	s_addc_u32 s79, s21, s61
	v_lshl_add_u64 v[154:155], v[166:167], 0, v[148:149]
	v_lshlrev_b64 v[148:149], 10, v[142:143]
	v_ashrrev_i32_e32 v141, 31, v140
	global_load_dwordx4 v[136:139], v146, s[78:79]
	v_lshl_add_u64 v[158:159], v[166:167], 0, v[148:149]
	v_lshlrev_b64 v[148:149], 10, v[140:141]
	v_lshl_add_u64 v[162:163], v[166:167], 0, v[148:149]
	global_load_dwordx2 v[160:161], v[150:151], off
	global_load_dwordx2 v[156:157], v[154:155], off
	global_load_dwordx2 v[152:153], v[158:159], off
	global_load_dwordx2 v[148:149], v[162:163], off
	s_waitcnt vmcnt(0)
	v_add_f32_e32 v147, v124, v132
	v_mul_f32_e32 v147, 0xbfb8aa3b, v147
	v_exp_f32_e32 v147, v147
	s_nop 0
	v_add_f32_e32 v147, 1.0, v147
	v_rcp_f32_e32 v147, v147
	s_nop 0
	v_mul_f32_e32 v147, v136, v147
	v_add_f32_e32 v164, v147, v147
	v_cmp_nlt_f32_e32 vcc, s4, v164
	v_mul_f32_e32 v252, 0x3fb8aa3b, v164
	v_exp_f32_e32 v252, v252
	v_fmamk_f32 v165, v164, 0x3ab60b61, v237
	v_fmaak_f32 v165, v164, v165, 0x3d2aaaab
	v_fmaak_f32 v165, v164, v165, 0x3e2aaaab
	v_fma_f32 v165, v164, v165, 0.5
	v_fma_f32 v165, v164, v165, 1.0
	v_mul_f32_e32 v169, v164, v165
	v_add_f32_e32 v252, -1.0, v252
	v_cndmask_b32_e32 v169, v169, v252, vcc
	v_add_f32_e32 v164, v125, v133
	v_mul_f32_e32 v164, 0xbfb8aa3b, v164
	v_exp_f32_e32 v164, v164
	s_nop 0
	v_add_f32_e32 v164, 1.0, v164
	v_rcp_f32_e32 v164, v164
	s_nop 0
	v_mul_f32_e32 v164, v137, v164
	v_add_f32_e32 v165, v164, v164
	v_cmp_nlt_f32_e32 vcc, s4, v165
	v_mul_f32_e32 v252, 0x3fb8aa3b, v165
	v_exp_f32_e32 v252, v252
	v_fmamk_f32 v168, v165, 0x3ab60b61, v237
	v_fmaak_f32 v168, v165, v168, 0x3d2aaaab
	v_fmaak_f32 v168, v165, v168, 0x3e2aaaab
	v_fma_f32 v168, v165, v168, 0.5
	v_fma_f32 v168, v165, v168, 1.0
	v_mul_f32_e32 v168, v165, v168
	v_add_f32_e32 v252, -1.0, v252
	v_cndmask_b32_e32 v168, v168, v252, vcc
	v_add_f32_e32 v165, v126, v134
	v_mul_f32_e32 v165, 0xbfb8aa3b, v165
	v_exp_f32_e32 v165, v165
	s_nop 0
	v_add_f32_e32 v165, 1.0, v165
	v_rcp_f32_e32 v165, v165
	s_nop 0
	v_mul_f32_e32 v165, v138, v165
	v_add_f32_e32 v170, v165, v165
	v_cmp_nlt_f32_e32 vcc, s4, v170
	v_mul_f32_e32 v252, 0x3fb8aa3b, v170
	v_exp_f32_e32 v252, v252
	v_fmamk_f32 v171, v170, 0x3ab60b61, v237
	v_fmaak_f32 v171, v170, v171, 0x3d2aaaab
	v_fmaak_f32 v171, v170, v171, 0x3e2aaaab
	v_fma_f32 v171, v170, v171, 0.5
	v_fma_f32 v171, v170, v171, 1.0
	v_mul_f32_e32 v172, v170, v171
	v_add_f32_e32 v252, -1.0, v252
	v_cndmask_b32_e32 v172, v172, v252, vcc
	v_add_f32_e32 v170, v127, v135
	v_mul_f32_e32 v170, 0xbfb8aa3b, v170
	v_exp_f32_e32 v170, v170
	s_nop 0
	v_add_f32_e32 v170, 1.0, v170
	v_rcp_f32_e32 v170, v170
	s_nop 0
	v_mul_f32_e32 v170, v139, v170
	v_add_f32_e32 v173, v170, v170
	v_cmp_nlt_f32_e32 vcc, s4, v173
	v_mul_f32_e32 v252, 0x3fb8aa3b, v173
	v_exp_f32_e32 v252, v252
	v_fmamk_f32 v171, v173, 0x3ab60b61, v237
	v_fmaak_f32 v171, v173, v171, 0x3d2aaaab
	v_fmaak_f32 v171, v173, v171, 0x3e2aaaab
	v_fma_f32 v171, v173, v171, 0.5
	v_fma_f32 v171, v173, v171, 1.0
	v_mul_f32_e32 v171, v173, v171
	v_add_f32_e32 v252, -1.0, v252
	v_cndmask_b32_e32 v171, v171, v252, vcc
	v_add_f32_e32 v173, v122, v130
	v_mul_f32_e32 v173, 0xbfb8aa3b, v173
	v_add_f32_e32 v175, v120, v128
	v_exp_f32_e32 v173, v173
	v_mul_f32_e32 v175, 0xbfb8aa3b, v175
	v_exp_f32_e32 v175, v175
	v_max_f32_e64 v172, -v172, -v172
	v_add_f32_e32 v173, 1.0, v173
	v_max_f32_e32 v172, 0, v172
	v_max_f32_e64 v169, -v169, -v169
	v_rcp_f32_e32 v173, v173
	v_sqrt_f32_e32 v172, v172
	v_add_f32_e32 v175, 1.0, v175
	v_max_f32_e32 v169, 0, v169
	v_rcp_f32_e32 v175, v175
	v_sqrt_f32_e32 v169, v169
	v_lshlrev_b32_e32 v174, 16, v161
	v_mul_f32_e32 v172, v173, v172
	v_mul_f32_e32 v172, v172, v174
	v_lshlrev_b32_e32 v174, 16, v160
	v_mul_f32_e32 v169, v175, v169
	v_mul_f32_e32 v169, v169, v174
	v_add_f32_e32 v174, v121, v129
	v_mul_f32_e32 v174, 0xbfb8aa3b, v174
	v_exp_f32_e32 v174, v174
	v_max_f32_e64 v168, -v168, -v168
	v_max_f32_e32 v168, 0, v168
	v_add_f32_e32 v173, v123, v131
	v_add_f32_e32 v174, 1.0, v174
	v_rcp_f32_e32 v174, v174
	v_sqrt_f32_e32 v168, v168
	v_mul_f32_e32 v173, 0xbfb8aa3b, v173
	v_exp_f32_e32 v173, v173
	v_and_b32_e32 v160, 0xffff0000, v160
	v_mul_f32_e32 v168, v174, v168
	v_mul_f32_e32 v168, v168, v160
	v_and_b32_e32 v160, 0xffff0000, v161
	v_max_f32_e64 v161, -v171, -v171
	v_add_f32_e32 v173, 1.0, v173
	v_max_f32_e32 v161, 0, v161
	v_rcp_f32_e32 v173, v173
	v_sqrt_f32_e32 v161, v161
	s_ashr_i32 s23, s22, 31
	s_lshl_b64 s[22:23], s[22:23], 24
	v_mul_f32_e32 v161, v173, v161
	v_mul_f32_e32 v171, v161, v160
	v_cvt_pk_bf16_f32 v160, v147, v164
	v_add_f32_e32 v147, v108, v132
	v_mul_f32_e32 v147, 0xbfb8aa3b, v147
	v_exp_f32_e32 v147, v147
	v_cvt_pk_bf16_f32 v164, v169, v168
; __device__ __forceinline__ unsigned cvt_pk_bf16(float lo, float hi) { const f32x2_t v = {lo, hi}; const bf16x2_t b = __builtin_convertvector(v, bf16x2_t); return __builtin_bit_cast(unsigned, b); }
; __device__ __forceinline__ float lo_bf(unsigned w) { return __uint_as_float(w << 16); }
; __device__ __forceinline__ float hi_bf(unsigned w) { return __uint_as_float(w & 0xffff0000u); }
; __device__ __forceinline__ float sigmoidf_(float x) { return __builtin_amdgcn_rcpf(1.0f + __builtin_amdgcn_exp2f(-1.4426950408889634f * x)); }
;     __device__ __forceinline__ void operator()(AccRef acc, const Unit& u, int wr, int wc, int fr, int fq) const {
;     ...
;                 for (int m = 0; m < 4; ++m) xwv[m] = *(const u32x2*)(xc + (size_t)(row0 + ai * HALF + m * 16) * 512 + ch);
; #pragma unroll
;                 for (int m = 0; m < 4; ++m) { const size_t row = (size_t)(row0 + ai * HALF + m * 16);
;                     const u32x2 xw = xwv[m];
;                     const float xv[4] = {lo_bf(xw.x), hi_bf(xw.x), lo_bf(xw.y), hi_bf(xw.y)};
;                     float la[4], uo[4];
; #pragma unroll
;                     for (int i = 0; i < 4; ++i) { const float r = sigmoidf_(acc[ai][bj][m][0][i] + vba[i]), gi = sigmoidf_(acc[ai][bj][m][1][i] + vbx[i]);
;                         const float l = cc[i] * r; la[i] = l; const float x2 = 2.0f * l;
;                         const float em1 = (x2 > -0.25f) ? x2 * (1.0f + x2 * (0.5f + x2 * (1.0f / 6.0f + x2 * (1.0f / 24.0f + x2 * (1.0f / 120.0f + x2 * (1.0f / 720.0f)))))) : (__expf(x2) - 1.0f);
;                         uo[i] = __builtin_amdgcn_sqrtf(fmaxf(-em1, 0.0f)) * gi * xv[i]; }
;                     u32x2 w0, w1; w0.x = cvt_pk_bf16(la[0], la[1]); w0.y = cvt_pk_bf16(la[2], la[3]); w1.x = cvt_pk_bf16(uo[0], uo[1]); w1.y = cvt_pk_bf16(uo[2], uo[3]);
;                     *(u32x2*)(loga + ((size_t)dir * MT + row) * 512 + ch) = w0; *(u32x2*)(uu + ((size_t)dir * MT + row) * 512 + ch) = w1; } } }
	v_lshlrev_b64 v[168:169], 9, v[218:219]
	v_lshl_add_u64 v[168:169], v[168:169], 0, s[22:23]
	v_add_f32_e32 v147, 1.0, v147
	v_rcp_f32_e32 v147, v147
	v_lshlrev_b64 v[168:169], 1, v[168:169]
	v_cvt_pk_bf16_f32 v161, v165, v170
	v_cvt_pk_bf16_f32 v165, v172, v171
	v_lshl_add_u64 v[170:171], s[44:45], 0, v[168:169]
	v_lshl_add_u64 v[182:183], v[170:171], 0, v[184:185]
	global_store_dwordx2 v[182:183], v[160:161], off
	v_lshl_add_u64 v[160:161], s[52:53], 0, v[168:169]
	v_mul_f32_e32 v147, v136, v147
	v_lshl_add_u64 v[222:223], v[160:161], 0, v[184:185]
	v_add_f32_e32 v160, v147, v147
	global_store_dwordx2 v[222:223], v[164:165], off
	v_cmp_nlt_f32_e32 vcc, s4, v160
	v_mul_f32_e32 v252, 0x3fb8aa3b, v160
	v_exp_f32_e32 v252, v252
	v_fmamk_f32 v161, v160, 0x3ab60b61, v237
	v_fmaak_f32 v161, v160, v161, 0x3d2aaaab
	v_fmaak_f32 v161, v160, v161, 0x3e2aaaab
	v_fma_f32 v161, v160, v161, 0.5
	v_fma_f32 v161, v160, v161, 1.0
	v_mul_f32_e32 v161, v160, v161
	v_add_f32_e32 v252, -1.0, v252
	v_cndmask_b32_e32 v161, v161, v252, vcc
	v_add_f32_e32 v160, v109, v133
	v_mul_f32_e32 v160, 0xbfb8aa3b, v160
	v_exp_f32_e32 v160, v160
	s_nop 0
	v_add_f32_e32 v160, 1.0, v160
	v_rcp_f32_e32 v160, v160
	s_nop 0
	v_mul_f32_e32 v160, v137, v160
	v_add_f32_e32 v164, v160, v160
	v_cmp_nlt_f32_e32 vcc, s4, v164
	v_mul_f32_e32 v252, 0x3fb8aa3b, v164
	v_exp_f32_e32 v252, v252
	v_fmamk_f32 v165, v164, 0x3ab60b61, v237
	v_fmaak_f32 v165, v164, v165, 0x3d2aaaab
	v_fmaak_f32 v165, v164, v165, 0x3e2aaaab
	v_fma_f32 v165, v164, v165, 0.5
	v_fma_f32 v165, v164, v165, 1.0
	v_mul_f32_e32 v165, v164, v165
	v_add_f32_e32 v252, -1.0, v252
	v_cndmask_b32_e32 v165, v165, v252, vcc
	v_add_f32_e32 v164, v110, v134
	v_mul_f32_e32 v164, 0xbfb8aa3b, v164
	v_exp_f32_e32 v164, v164
	s_nop 0
	v_add_f32_e32 v164, 1.0, v164
	v_rcp_f32_e32 v164, v164
	s_nop 0
	v_mul_f32_e32 v164, v138, v164
	v_add_f32_e32 v168, v164, v164
	v_cmp_nlt_f32_e32 vcc, s4, v168
	v_mul_f32_e32 v252, 0x3fb8aa3b, v168
	v_exp_f32_e32 v252, v252
	v_fmamk_f32 v169, v168, 0x3ab60b61, v237
	v_fmaak_f32 v169, v168, v169, 0x3d2aaaab
	v_fmaak_f32 v169, v168, v169, 0x3e2aaaab
	v_fma_f32 v169, v168, v169, 0.5
	v_fma_f32 v169, v168, v169, 1.0
	v_mul_f32_e32 v170, v168, v169
	v_add_f32_e32 v252, -1.0, v252
	v_cndmask_b32_e32 v170, v170, v252, vcc
	v_add_f32_e32 v168, v111, v135
	v_mul_f32_e32 v168, 0xbfb8aa3b, v168
	v_exp_f32_e32 v168, v168
	s_nop 0
	v_add_f32_e32 v168, 1.0, v168
	v_rcp_f32_e32 v168, v168
	s_nop 0
	v_mul_f32_e32 v168, v139, v168
	v_add_f32_e32 v171, v168, v168
	v_cmp_nlt_f32_e32 vcc, s4, v171
	v_mul_f32_e32 v252, 0x3fb8aa3b, v171
	v_exp_f32_e32 v252, v252
	v_fmamk_f32 v169, v171, 0x3ab60b61, v237
	v_fmaak_f32 v169, v171, v169, 0x3d2aaaab
	v_fmaak_f32 v169, v171, v169, 0x3e2aaaab
	v_fma_f32 v169, v171, v169, 0.5
	v_fma_f32 v169, v171, v169, 1.0
	v_mul_f32_e32 v169, v171, v169
	v_add_f32_e32 v252, -1.0, v252
	v_cndmask_b32_e32 v169, v169, v252, vcc
	v_add_f32_e32 v171, v106, v130
	v_mul_f32_e32 v171, 0xbfb8aa3b, v171
	v_add_f32_e32 v173, v104, v128
	v_exp_f32_e32 v171, v171
	v_mul_f32_e32 v173, 0xbfb8aa3b, v173
	v_exp_f32_e32 v173, v173
	v_max_f32_e64 v170, -v170, -v170
	v_add_f32_e32 v171, 1.0, v171
	v_max_f32_e32 v170, 0, v170
	v_max_f32_e64 v161, -v161, -v161
	v_rcp_f32_e32 v171, v171
	v_sqrt_f32_e32 v170, v170
	v_add_f32_e32 v173, 1.0, v173
	v_max_f32_e32 v161, 0, v161
	v_rcp_f32_e32 v173, v173
	v_sqrt_f32_e32 v161, v161
	v_lshlrev_b32_e32 v172, 16, v157
	v_mul_f32_e32 v170, v171, v170
	v_mul_f32_e32 v170, v170, v172
	v_lshlrev_b32_e32 v172, 16, v156
	v_mul_f32_e32 v161, v173, v161
	v_mul_f32_e32 v161, v161, v172
	v_add_f32_e32 v172, v105, v129
	v_mul_f32_e32 v172, 0xbfb8aa3b, v172
	v_exp_f32_e32 v172, v172
	v_max_f32_e64 v165, -v165, -v165
	v_max_f32_e32 v165, 0, v165
	v_add_f32_e32 v171, v107, v131
	v_add_f32_e32 v172, 1.0, v172
	v_rcp_f32_e32 v172, v172
	v_sqrt_f32_e32 v165, v165
	v_mul_f32_e32 v171, 0xbfb8aa3b, v171
	v_exp_f32_e32 v171, v171
	v_and_b32_e32 v156, 0xffff0000, v156
	v_mul_f32_e32 v165, v172, v165
	v_mul_f32_e32 v165, v165, v156
	v_and_b32_e32 v156, 0xffff0000, v157
	v_max_f32_e64 v157, -v169, -v169
	v_add_f32_e32 v171, 1.0, v171
	v_max_f32_e32 v157, 0, v157
	v_rcp_f32_e32 v171, v171
	v_sqrt_f32_e32 v157, v157
	s_nop 0
	v_mul_f32_e32 v157, v171, v157
	v_mul_f32_e32 v169, v157, v156
	v_cvt_pk_bf16_f32 v156, v147, v160
	v_cvt_pk_bf16_f32 v157, v164, v168
	v_cvt_pk_bf16_f32 v160, v161, v165
	v_lshlrev_b64 v[164:165], 9, v[144:145]
	v_add_f32_e32 v145, v92, v132
	v_mul_f32_e32 v145, 0xbfb8aa3b, v145
	v_exp_f32_e32 v145, v145
	v_lshl_add_u64 v[164:165], v[164:165], 0, s[22:23]
	v_lshlrev_b64 v[164:165], 1, v[164:165]
	v_cvt_pk_bf16_f32 v161, v170, v169
	v_add_f32_e32 v145, 1.0, v145
	v_rcp_f32_e32 v145, v145
	v_lshl_add_u64 v[168:169], s[44:45], 0, v[164:165]
	v_lshl_add_u64 v[224:225], v[168:169], 0, v[184:185]
	global_store_dwordx2 v[224:225], v[156:157], off
	v_mul_f32_e32 v145, v136, v145
	v_lshl_add_u64 v[156:157], s[52:53], 0, v[164:165]
	v_add_f32_e32 v147, v145, v145
	v_lshl_add_u64 v[226:227], v[156:157], 0, v[184:185]
	global_store_dwordx2 v[226:227], v[160:161], off
	v_cmp_nlt_f32_e32 vcc, s4, v147
	v_mul_f32_e32 v252, 0x3fb8aa3b, v147
	v_exp_f32_e32 v252, v252
	v_fmamk_f32 v156, v147, 0x3ab60b61, v237
	v_fmaak_f32 v156, v147, v156, 0x3d2aaaab
	v_fmaak_f32 v156, v147, v156, 0x3e2aaaab
	v_fma_f32 v156, v147, v156, 0.5
	v_fma_f32 v156, v147, v156, 1.0
	v_mul_f32_e32 v156, v147, v156
	v_add_f32_e32 v252, -1.0, v252
	v_cndmask_b32_e32 v156, v156, v252, vcc
	v_add_f32_e32 v147, v93, v133
	v_mul_f32_e32 v147, 0xbfb8aa3b, v147
	v_exp_f32_e32 v147, v147
	s_nop 0
	v_add_f32_e32 v147, 1.0, v147
; __device__ __forceinline__ unsigned cvt_pk_bf16(float lo, float hi) { const f32x2_t v = {lo, hi}; const bf16x2_t b = __builtin_convertvector(v, bf16x2_t); return __builtin_bit_cast(unsigned, b); }
; __device__ __forceinline__ float lo_bf(unsigned w) { return __uint_as_float(w << 16); }
; __device__ __forceinline__ float hi_bf(unsigned w) { return __uint_as_float(w & 0xffff0000u); }
; __device__ __forceinline__ float sigmoidf_(float x) { return __builtin_amdgcn_rcpf(1.0f + __builtin_amdgcn_exp2f(-1.4426950408889634f * x)); }
;     __device__ __forceinline__ void operator()(AccRef acc, const Unit& u, int wr, int wc, int fr, int fq) const {
;     ...
;                 for (int m = 0; m < 4; ++m) { const size_t row = (size_t)(row0 + ai * HALF + m * 16);
;                     const u32x2 xw = xwv[m];
;                     const float xv[4] = {lo_bf(xw.x), hi_bf(xw.x), lo_bf(xw.y), hi_bf(xw.y)};
;                     float la[4], uo[4];
; #pragma unroll
;                     for (int i = 0; i < 4; ++i) { const float r = sigmoidf_(acc[ai][bj][m][0][i] + vba[i]), gi = sigmoidf_(acc[ai][bj][m][1][i] + vbx[i]);
;                         const float l = cc[i] * r; la[i] = l; const float x2 = 2.0f * l;
;                         const float em1 = (x2 > -0.25f) ? x2 * (1.0f + x2 * (0.5f + x2 * (1.0f / 6.0f + x2 * (1.0f / 24.0f + x2 * (1.0f / 120.0f + x2 * (1.0f / 720.0f)))))) : (__expf(x2) - 1.0f);
;                         uo[i] = __builtin_amdgcn_sqrtf(fmaxf(-em1, 0.0f)) * gi * xv[i]; }
;                     u32x2 w0, w1; w0.x = cvt_pk_bf16(la[0], la[1]); w0.y = cvt_pk_bf16(la[2], la[3]); w1.x = cvt_pk_bf16(uo[0], uo[1]); w1.y = cvt_pk_bf16(uo[2], uo[3]);
;                     *(u32x2*)(loga + ((size_t)dir * MT + row) * 512 + ch) = w0; *(u32x2*)(uu + ((size_t)dir * MT + row) * 512 + ch) = w1; } } }
	v_rcp_f32_e32 v147, v147
	s_nop 0
	v_mul_f32_e32 v147, v137, v147
	v_add_f32_e32 v157, v147, v147
	v_cmp_nlt_f32_e32 vcc, s4, v157
	v_mul_f32_e32 v252, 0x3fb8aa3b, v157
	v_exp_f32_e32 v252, v252
	v_fmamk_f32 v160, v157, 0x3ab60b61, v237
	v_fmaak_f32 v160, v157, v160, 0x3d2aaaab
	v_fmaak_f32 v160, v157, v160, 0x3e2aaaab
	v_fma_f32 v160, v157, v160, 0.5
	v_fma_f32 v160, v157, v160, 1.0
	v_mul_f32_e32 v160, v157, v160
	v_add_f32_e32 v252, -1.0, v252
	v_cndmask_b32_e32 v160, v160, v252, vcc
	v_add_f32_e32 v157, v94, v134
	v_mul_f32_e32 v157, 0xbfb8aa3b, v157
	v_exp_f32_e32 v157, v157
	s_nop 0
	v_add_f32_e32 v157, 1.0, v157
	v_rcp_f32_e32 v157, v157
	s_nop 0
	v_mul_f32_e32 v157, v138, v157
	v_add_f32_e32 v161, v157, v157
	v_cmp_nlt_f32_e32 vcc, s4, v161
	v_mul_f32_e32 v252, 0x3fb8aa3b, v161
	v_exp_f32_e32 v252, v252
	v_fmamk_f32 v164, v161, 0x3ab60b61, v237
	v_fmaak_f32 v164, v161, v164, 0x3d2aaaab
	v_fmaak_f32 v164, v161, v164, 0x3e2aaaab
	v_fma_f32 v164, v161, v164, 0.5
	v_fma_f32 v164, v161, v164, 1.0
	v_mul_f32_e32 v165, v161, v164
	v_add_f32_e32 v252, -1.0, v252
	v_cndmask_b32_e32 v165, v165, v252, vcc
	v_add_f32_e32 v161, v95, v135
	v_mul_f32_e32 v161, 0xbfb8aa3b, v161
	v_exp_f32_e32 v161, v161
	s_nop 0
	v_add_f32_e32 v161, 1.0, v161
	v_rcp_f32_e32 v161, v161
	s_nop 0
	v_mul_f32_e32 v161, v139, v161
	v_add_f32_e32 v168, v161, v161
	v_cmp_nlt_f32_e32 vcc, s4, v168
	v_mul_f32_e32 v252, 0x3fb8aa3b, v168
	v_exp_f32_e32 v252, v252
	v_fmamk_f32 v164, v168, 0x3ab60b61, v237
	v_fmaak_f32 v164, v168, v164, 0x3d2aaaab
	v_fmaak_f32 v164, v168, v164, 0x3e2aaaab
	v_fma_f32 v164, v168, v164, 0.5
	v_fma_f32 v164, v168, v164, 1.0
	v_mul_f32_e32 v164, v168, v164
	v_add_f32_e32 v252, -1.0, v252
	v_cndmask_b32_e32 v164, v164, v252, vcc
	v_add_f32_e32 v168, v90, v130
	v_mul_f32_e32 v168, 0xbfb8aa3b, v168
	v_add_f32_e32 v170, v88, v128
	v_exp_f32_e32 v168, v168
	v_mul_f32_e32 v170, 0xbfb8aa3b, v170
	v_exp_f32_e32 v170, v170
	v_max_f32_e64 v165, -v165, -v165
	v_add_f32_e32 v168, 1.0, v168
	v_max_f32_e32 v165, 0, v165
	v_max_f32_e64 v156, -v156, -v156
	v_rcp_f32_e32 v168, v168
	v_sqrt_f32_e32 v165, v165
	v_add_f32_e32 v170, 1.0, v170
	v_max_f32_e32 v156, 0, v156
	v_rcp_f32_e32 v170, v170
	v_sqrt_f32_e32 v156, v156
	v_lshlrev_b32_e32 v169, 16, v153
	v_mul_f32_e32 v165, v168, v165
	v_mul_f32_e32 v165, v165, v169
	v_lshlrev_b32_e32 v169, 16, v152
	v_mul_f32_e32 v156, v170, v156
	v_mul_f32_e32 v156, v156, v169
	v_add_f32_e32 v169, v89, v129
	v_mul_f32_e32 v169, 0xbfb8aa3b, v169
	v_exp_f32_e32 v169, v169
	v_max_f32_e64 v160, -v160, -v160
	v_max_f32_e32 v160, 0, v160
	v_add_f32_e32 v168, v91, v131
	v_add_f32_e32 v169, 1.0, v169
	v_rcp_f32_e32 v169, v169
	v_sqrt_f32_e32 v160, v160
	v_mul_f32_e32 v168, 0xbfb8aa3b, v168
	v_exp_f32_e32 v168, v168
	v_and_b32_e32 v152, 0xffff0000, v152
	v_mul_f32_e32 v160, v169, v160
	v_mul_f32_e32 v160, v160, v152
	v_and_b32_e32 v152, 0xffff0000, v153
	v_max_f32_e64 v153, -v164, -v164
	v_add_f32_e32 v168, 1.0, v168
	v_max_f32_e32 v153, 0, v153
	v_rcp_f32_e32 v168, v168
	v_sqrt_f32_e32 v153, v153
	v_cvt_pk_bf16_f32 v156, v156, v160
	v_mul_f32_e32 v153, v168, v153
	v_mul_f32_e32 v164, v153, v152
	v_cvt_pk_bf16_f32 v153, v157, v161
	v_lshlrev_b64 v[160:161], 9, v[142:143]
	v_add_f32_e32 v143, v76, v132
	v_mul_f32_e32 v143, 0xbfb8aa3b, v143
	v_exp_f32_e32 v143, v143
	v_lshl_add_u64 v[160:161], v[160:161], 0, s[22:23]
	v_lshlrev_b64 v[160:161], 1, v[160:161]
	v_cvt_pk_bf16_f32 v157, v165, v164
	v_add_f32_e32 v143, 1.0, v143
	v_rcp_f32_e32 v143, v143
	v_lshl_add_u64 v[164:165], s[44:45], 0, v[160:161]
	v_cvt_pk_bf16_f32 v152, v145, v147
	v_lshl_add_u64 v[228:229], v[164:165], 0, v[184:185]
	v_mul_f32_e32 v143, v136, v143
	global_store_dwordx2 v[228:229], v[152:153], off
	v_lshl_add_u64 v[152:153], s[52:53], 0, v[160:161]
	v_add_f32_e32 v147, v143, v143
	v_lshl_add_u64 v[230:231], v[152:153], 0, v[184:185]
	global_store_dwordx2 v[230:231], v[156:157], off
	v_cmp_nlt_f32_e32 vcc, s4, v147
	v_mul_f32_e32 v252, 0x3fb8aa3b, v147
	v_exp_f32_e32 v252, v252
	v_fmamk_f32 v145, v147, 0x3ab60b61, v237
	v_fmaak_f32 v145, v147, v145, 0x3d2aaaab
	v_fmaak_f32 v145, v147, v145, 0x3e2aaaab
	v_fma_f32 v145, v147, v145, 0.5
	v_fma_f32 v145, v147, v145, 1.0
	v_mul_f32_e32 v145, v147, v145
	v_add_f32_e32 v252, -1.0, v252
	v_cndmask_b32_e32 v145, v145, v252, vcc
	v_add_f32_e32 v147, v77, v133
	v_mul_f32_e32 v147, 0xbfb8aa3b, v147
	v_exp_f32_e32 v147, v147
	s_nop 0
	v_add_f32_e32 v147, 1.0, v147
	v_rcp_f32_e32 v147, v147
	s_nop 0
	v_mul_f32_e32 v147, v137, v147
	v_add_f32_e32 v153, v147, v147
	v_cmp_nlt_f32_e32 vcc, s4, v153
	v_mul_f32_e32 v252, 0x3fb8aa3b, v153
	v_exp_f32_e32 v252, v252
	v_fmamk_f32 v152, v153, 0x3ab60b61, v237
	v_fmaak_f32 v152, v153, v152, 0x3d2aaaab
	v_fmaak_f32 v152, v153, v152, 0x3e2aaaab
	v_fma_f32 v152, v153, v152, 0.5
	v_fma_f32 v152, v153, v152, 1.0
	v_mul_f32_e32 v152, v153, v152
	v_add_f32_e32 v252, -1.0, v252
	v_cndmask_b32_e32 v152, v152, v252, vcc
	v_add_f32_e32 v153, v78, v134
	v_mul_f32_e32 v153, 0xbfb8aa3b, v153
	v_exp_f32_e32 v153, v153
	s_nop 0
	v_add_f32_e32 v153, 1.0, v153
	v_rcp_f32_e32 v153, v153
	s_nop 0
	v_mul_f32_e32 v153, v138, v153
	v_add_f32_e32 v156, v153, v153
	v_cmp_nlt_f32_e32 vcc, s4, v156
	v_mul_f32_e32 v252, 0x3fb8aa3b, v156
	v_exp_f32_e32 v252, v252
	v_fmamk_f32 v157, v156, 0x3ab60b61, v237
	v_fmaak_f32 v157, v156, v157, 0x3d2aaaab
	v_fmaak_f32 v157, v156, v157, 0x3e2aaaab
	v_fma_f32 v157, v156, v157, 0.5
	v_fma_f32 v157, v156, v157, 1.0
	v_mul_f32_e32 v160, v156, v157
	v_add_f32_e32 v252, -1.0, v252
	v_cndmask_b32_e32 v160, v160, v252, vcc
	v_add_f32_e32 v156, v79, v135
	v_mul_f32_e32 v156, 0xbfb8aa3b, v156
; __device__ __forceinline__ unsigned cvt_pk_bf16(float lo, float hi) { const f32x2_t v = {lo, hi}; const bf16x2_t b = __builtin_convertvector(v, bf16x2_t); return __builtin_bit_cast(unsigned, b); }
; __device__ __forceinline__ float lo_bf(unsigned w) { return __uint_as_float(w << 16); }
; __device__ __forceinline__ float hi_bf(unsigned w) { return __uint_as_float(w & 0xffff0000u); }
; __device__ __forceinline__ float sigmoidf_(float x) { return __builtin_amdgcn_rcpf(1.0f + __builtin_amdgcn_exp2f(-1.4426950408889634f * x)); }
;     __device__ __forceinline__ void operator()(AccRef acc, const Unit& u, int wr, int wc, int fr, int fq) const {
;     ...
;                 for (int m = 0; m < 4; ++m) xwv[m] = *(const u32x2*)(xc + (size_t)(row0 + ai * HALF + m * 16) * 512 + ch);
; #pragma unroll
;                 for (int m = 0; m < 4; ++m) { const size_t row = (size_t)(row0 + ai * HALF + m * 16);
;                     const u32x2 xw = xwv[m];
;                     const float xv[4] = {lo_bf(xw.x), hi_bf(xw.x), lo_bf(xw.y), hi_bf(xw.y)};
;                     float la[4], uo[4];
; #pragma unroll
;                     for (int i = 0; i < 4; ++i) { const float r = sigmoidf_(acc[ai][bj][m][0][i] + vba[i]), gi = sigmoidf_(acc[ai][bj][m][1][i] + vbx[i]);
;                         const float l = cc[i] * r; la[i] = l; const float x2 = 2.0f * l;
;                         const float em1 = (x2 > -0.25f) ? x2 * (1.0f + x2 * (0.5f + x2 * (1.0f / 6.0f + x2 * (1.0f / 24.0f + x2 * (1.0f / 120.0f + x2 * (1.0f / 720.0f)))))) : (__expf(x2) - 1.0f);
;                         uo[i] = __builtin_amdgcn_sqrtf(fmaxf(-em1, 0.0f)) * gi * xv[i]; }
;                     u32x2 w0, w1; w0.x = cvt_pk_bf16(la[0], la[1]); w0.y = cvt_pk_bf16(la[2], la[3]); w1.x = cvt_pk_bf16(uo[0], uo[1]); w1.y = cvt_pk_bf16(uo[2], uo[3]);
	v_exp_f32_e32 v156, v156
	s_nop 0
	v_add_f32_e32 v156, 1.0, v156
	v_rcp_f32_e32 v156, v156
	s_nop 0
	v_mul_f32_e32 v156, v139, v156
	v_add_f32_e32 v161, v156, v156
	v_cmp_nlt_f32_e32 vcc, s4, v161
	v_mul_f32_e32 v252, 0x3fb8aa3b, v161
	v_exp_f32_e32 v252, v252
	v_fmamk_f32 v157, v161, 0x3ab60b61, v237
	v_fmaak_f32 v157, v161, v157, 0x3d2aaaab
	v_fmaak_f32 v157, v161, v157, 0x3e2aaaab
	v_fma_f32 v157, v161, v157, 0.5
	v_fma_f32 v157, v161, v157, 1.0
	v_mul_f32_e32 v157, v161, v157
	v_add_f32_e32 v252, -1.0, v252
	v_cndmask_b32_e32 v157, v157, v252, vcc
	v_add_f32_e32 v161, v74, v130
	v_mul_f32_e32 v161, 0xbfb8aa3b, v161
	v_exp_f32_e32 v161, v161
	v_max_f32_e64 v160, -v160, -v160
	v_max_f32_e32 v160, 0, v160
	v_sqrt_f32_e32 v160, v160
	v_add_f32_e32 v161, 1.0, v161
	v_rcp_f32_e32 v161, v161
	v_add_f32_e32 v165, v75, v131
	v_mul_f32_e32 v165, 0xbfb8aa3b, v165
	v_lshlrev_b32_e32 v164, 16, v149
	v_mul_f32_e32 v160, v161, v160
	v_exp_f32_e32 v161, v165
	v_add_f32_e32 v165, v72, v128
	v_mul_f32_e32 v165, 0xbfb8aa3b, v165
	v_exp_f32_e32 v165, v165
	v_mul_f32_e32 v160, v160, v164
	v_max_f32_e64 v145, -v145, -v145
	v_max_f32_e32 v145, 0, v145
	v_add_f32_e32 v164, 1.0, v165
	v_add_f32_e32 v165, v73, v129
	v_mul_f32_e32 v165, 0xbfb8aa3b, v165
	v_rcp_f32_e32 v164, v164
	v_sqrt_f32_e32 v145, v145
	v_exp_f32_e32 v165, v165
	v_max_f32_e64 v152, -v152, -v152
	v_max_f32_e32 v152, 0, v152
	v_mul_f32_e32 v145, v164, v145
	v_add_f32_e32 v164, 1.0, v165
	v_max_f32_e64 v157, -v157, -v157
	v_add_f32_e32 v161, 1.0, v161
	v_rcp_f32_e32 v164, v164
	v_sqrt_f32_e32 v152, v152
	v_max_f32_e32 v157, 0, v157
	v_rcp_f32_e32 v161, v161
	v_sqrt_f32_e32 v157, v157
	v_lshlrev_b32_e32 v168, 16, v148
	v_and_b32_e32 v148, 0xffff0000, v148
	v_mul_f32_e32 v152, v164, v152
	v_mul_f32_e32 v148, v152, v148
	v_and_b32_e32 v149, 0xffff0000, v149
	v_mul_f32_e32 v152, v161, v157
	v_mul_f32_e32 v145, v145, v168
	v_mul_f32_e32 v149, v152, v149
	v_cvt_pk_bf16_f32 v153, v153, v156
	v_cvt_pk_bf16_f32 v156, v145, v148
	v_cvt_pk_bf16_f32 v157, v160, v149
	v_lshlrev_b64 v[148:149], 9, v[140:141]
	v_lshl_add_u64 v[148:149], v[148:149], 0, s[22:23]
	v_lshlrev_b64 v[160:161], 1, v[148:149]
	v_lshl_add_u64 v[148:149], s[44:45], 0, v[160:161]
	v_cvt_pk_bf16_f32 v152, v143, v147
	v_lshl_add_u64 v[148:149], v[148:149], 0, v[184:185]
	global_store_dwordx2 v[148:149], v[152:153], off
	v_lshl_add_u64 v[152:153], s[52:53], 0, v[160:161]
	v_add_u32_e32 v168, 0x80, v218
	v_lshl_add_u64 v[152:153], v[152:153], 0, v[184:185]
	v_ashrrev_i32_e32 v169, 31, v168
	v_add_u32_e32 v172, 0x90, v218
	v_add_u32_e32 v176, 0xa0, v218
	v_add_u32_e32 v180, 0xb0, v218
	global_store_dwordx2 v[152:153], v[156:157], off
	v_lshlrev_b64 v[156:157], 10, v[168:169]
	v_ashrrev_i32_e32 v173, 31, v172
	v_ashrrev_i32_e32 v177, 31, v176
	v_ashrrev_i32_e32 v181, 31, v180
	v_lshl_add_u64 v[156:157], v[166:167], 0, v[156:157]
	v_lshlrev_b64 v[160:161], 10, v[172:173]
	v_lshlrev_b64 v[164:165], 10, v[176:177]
	v_lshlrev_b64 v[170:171], 10, v[180:181]
	v_lshl_add_u64 v[160:161], v[166:167], 0, v[160:161]
	v_lshl_add_u64 v[164:165], v[166:167], 0, v[164:165]
	v_lshl_add_u64 v[166:167], v[166:167], 0, v[170:171]
	global_load_dwordx2 v[170:171], v[156:157], off
	global_load_dwordx2 v[174:175], v[160:161], off
	global_load_dwordx2 v[178:179], v[164:165], off
	global_load_dwordx2 v[220:221], v[166:167], off
	v_add_f32_e32 v141, v60, v132
	v_mul_f32_e32 v141, 0xbfb8aa3b, v141
	v_exp_f32_e32 v141, v141
	s_nop 0
	v_add_f32_e32 v141, 1.0, v141
	v_rcp_f32_e32 v141, v141
	s_nop 0
	v_mul_f32_e32 v141, v136, v141
	v_add_f32_e32 v143, v141, v141
	v_cmp_nlt_f32_e32 vcc, s4, v143
	v_mul_f32_e32 v252, 0x3fb8aa3b, v143
	v_exp_f32_e32 v252, v252
	v_fmamk_f32 v145, v143, 0x3ab60b61, v237
	v_fmaak_f32 v145, v143, v145, 0x3d2aaaab
	v_fmaak_f32 v145, v143, v145, 0x3e2aaaab
	v_fma_f32 v145, v143, v145, 0.5
	v_fma_f32 v145, v143, v145, 1.0
	v_mul_f32_e32 v145, v143, v145
	v_add_f32_e32 v252, -1.0, v252
	v_cndmask_b32_e32 v145, v145, v252, vcc
	v_add_f32_e32 v143, v61, v133
	v_mul_f32_e32 v143, 0xbfb8aa3b, v143
	v_exp_f32_e32 v143, v143
	s_nop 0
	v_add_f32_e32 v143, 1.0, v143
	v_rcp_f32_e32 v143, v143
	s_nop 0
	v_mul_f32_e32 v143, v137, v143
	v_add_f32_e32 v147, v143, v143
	v_cmp_nlt_f32_e32 vcc, s4, v147
	v_mul_f32_e32 v252, 0x3fb8aa3b, v147
	v_exp_f32_e32 v252, v252
	v_fmamk_f32 v219, v147, 0x3ab60b61, v237
	v_fmaak_f32 v219, v147, v219, 0x3d2aaaab
	v_fmaak_f32 v219, v147, v219, 0x3e2aaaab
	v_fma_f32 v219, v147, v219, 0.5
	v_fma_f32 v219, v147, v219, 1.0
	v_mul_f32_e32 v219, v147, v219
	v_add_f32_e32 v252, -1.0, v252
	v_cndmask_b32_e32 v219, v219, v252, vcc
	v_add_f32_e32 v147, v62, v134
	v_mul_f32_e32 v147, 0xbfb8aa3b, v147
	v_exp_f32_e32 v147, v147
	s_nop 0
	v_add_f32_e32 v147, 1.0, v147
	v_rcp_f32_e32 v147, v147
	s_nop 0
	v_mul_f32_e32 v147, v138, v147
	v_add_f32_e32 v232, v147, v147
	v_cmp_nlt_f32_e32 vcc, s4, v232
	v_mul_f32_e32 v252, 0x3fb8aa3b, v232
	v_exp_f32_e32 v252, v252
	v_fmamk_f32 v233, v232, 0x3ab60b61, v237
	v_fmaak_f32 v233, v232, v233, 0x3d2aaaab
	v_fmaak_f32 v233, v232, v233, 0x3e2aaaab
	v_fma_f32 v233, v232, v233, 0.5
	v_fma_f32 v233, v232, v233, 1.0
	v_mul_f32_e32 v249, v232, v233
	v_add_f32_e32 v252, -1.0, v252
	v_cndmask_b32_e32 v249, v249, v252, vcc
	v_add_f32_e32 v232, v63, v135
	v_mul_f32_e32 v232, 0xbfb8aa3b, v232
	v_exp_f32_e32 v232, v232
	s_nop 0
	v_add_f32_e32 v232, 1.0, v232
	v_rcp_f32_e32 v232, v232
	s_nop 0
	v_mul_f32_e32 v232, v139, v232
	v_add_f32_e32 v250, v232, v232
	v_cmp_nlt_f32_e32 vcc, s4, v250
	v_mul_f32_e32 v252, 0x3fb8aa3b, v250
	v_exp_f32_e32 v252, v252
	v_fmamk_f32 v233, v250, 0x3ab60b61, v237
	v_fmaak_f32 v233, v250, v233, 0x3d2aaaab
	v_fmaak_f32 v233, v250, v233, 0x3e2aaaab
	v_fma_f32 v233, v250, v233, 0.5
	v_fma_f32 v233, v250, v233, 1.0
	v_mul_f32_e32 v233, v250, v233
	v_add_f32_e32 v252, -1.0, v252
	v_cndmask_b32_e32 v233, v233, v252, vcc
	v_add_f32_e32 v238, v58, v130
	v_add_f32_e32 v241, v56, v128
	v_mul_f32_e32 v238, 0xbfb8aa3b, v238
	v_mul_f32_e32 v241, 0xbfb8aa3b, v241
	v_exp_f32_e32 v238, v238
	v_exp_f32_e32 v241, v241
	v_max_f32_e64 v240, -v249, -v249
	v_max_f32_e64 v145, -v145, -v145
	v_add_f32_e32 v238, 1.0, v238
	v_max_f32_e32 v240, 0, v240
	v_add_f32_e32 v241, 1.0, v241
	v_max_f32_e32 v145, 0, v145
	v_rcp_f32_e32 v238, v238
	v_sqrt_f32_e32 v240, v240
	v_rcp_f32_e32 v241, v241
	v_sqrt_f32_e32 v145, v145
	v_max_f32_e64 v219, -v219, -v219
	v_mul_f32_e32 v238, v238, v240
	s_waitcnt vmcnt(3)
; __device__ __forceinline__ unsigned cvt_pk_bf16(float lo, float hi) { const f32x2_t v = {lo, hi}; const bf16x2_t b = __builtin_convertvector(v, bf16x2_t); return __builtin_bit_cast(unsigned, b); }
; __device__ __forceinline__ float lo_bf(unsigned w) { return __uint_as_float(w << 16); }
; __device__ __forceinline__ float hi_bf(unsigned w) { return __uint_as_float(w & 0xffff0000u); }
; __device__ __forceinline__ float sigmoidf_(float x) { return __builtin_amdgcn_rcpf(1.0f + __builtin_amdgcn_exp2f(-1.4426950408889634f * x)); }
;     __device__ __forceinline__ void operator()(AccRef acc, const Unit& u, int wr, int wc, int fr, int fq) const {
;     ...
;                 for (int m = 0; m < 4; ++m) { const size_t row = (size_t)(row0 + ai * HALF + m * 16);
;                     const u32x2 xw = xwv[m];
;                     const float xv[4] = {lo_bf(xw.x), hi_bf(xw.x), lo_bf(xw.y), hi_bf(xw.y)};
;                     float la[4], uo[4];
; #pragma unroll
;                     for (int i = 0; i < 4; ++i) { const float r = sigmoidf_(acc[ai][bj][m][0][i] + vba[i]), gi = sigmoidf_(acc[ai][bj][m][1][i] + vbx[i]);
;                         const float l = cc[i] * r; la[i] = l; const float x2 = 2.0f * l;
;                         const float em1 = (x2 > -0.25f) ? x2 * (1.0f + x2 * (0.5f + x2 * (1.0f / 6.0f + x2 * (1.0f / 24.0f + x2 * (1.0f / 120.0f + x2 * (1.0f / 720.0f)))))) : (__expf(x2) - 1.0f);
;                         uo[i] = __builtin_amdgcn_sqrtf(fmaxf(-em1, 0.0f)) * gi * xv[i]; }
;                     u32x2 w0, w1; w0.x = cvt_pk_bf16(la[0], la[1]); w0.y = cvt_pk_bf16(la[2], la[3]); w1.x = cvt_pk_bf16(uo[0], uo[1]); w1.y = cvt_pk_bf16(uo[2], uo[3]);
;                     *(u32x2*)(loga + ((size_t)dir * MT + row) * 512 + ch) = w0; *(u32x2*)(uu + ((size_t)dir * MT + row) * 512 + ch) = w1; } } }
	v_lshlrev_b32_e32 v240, 16, v170
	v_mul_f32_e32 v145, v241, v145
	v_mul_f32_e32 v145, v145, v240
	v_add_f32_e32 v240, v57, v129
	v_mul_f32_e32 v240, 0xbfb8aa3b, v240
	v_exp_f32_e32 v240, v240
	v_lshlrev_b32_e32 v239, 16, v171
	v_max_f32_e32 v219, 0, v219
	v_mul_f32_e32 v238, v238, v239
	v_add_f32_e32 v240, 1.0, v240
	v_add_f32_e32 v239, v59, v131
	v_rcp_f32_e32 v240, v240
	v_sqrt_f32_e32 v219, v219
	v_mul_f32_e32 v239, 0xbfb8aa3b, v239
	v_exp_f32_e32 v239, v239
	v_and_b32_e32 v170, 0xffff0000, v170
	v_mul_f32_e32 v219, v240, v219
	v_mul_f32_e32 v219, v219, v170
	v_and_b32_e32 v170, 0xffff0000, v171
	v_max_f32_e64 v171, -v233, -v233
	v_add_f32_e32 v239, 1.0, v239
	v_max_f32_e32 v171, 0, v171
	v_rcp_f32_e32 v239, v239
	v_sqrt_f32_e32 v171, v171
	v_lshlrev_b64 v[168:169], 9, v[168:169]
	v_lshl_add_u64 v[168:169], v[168:169], 0, s[22:23]
	v_lshlrev_b64 v[250:251], 1, v[168:169]
	v_mul_f32_e32 v171, v239, v171
	v_mul_f32_e32 v233, v171, v170
	v_cvt_pk_bf16_f32 v170, v141, v143
	v_add_f32_e32 v141, v44, v132
	v_mul_f32_e32 v141, 0xbfb8aa3b, v141
	v_exp_f32_e32 v141, v141
	v_lshl_add_u64 v[168:169], s[44:45], 0, v[250:251]
	v_cvt_pk_bf16_f32 v171, v147, v232
	v_lshl_add_u64 v[168:169], v[168:169], 0, v[184:185]
	v_add_f32_e32 v141, 1.0, v141
	v_rcp_f32_e32 v141, v141
	global_store_dwordx2 v[168:169], v[170:171], off
	v_lshl_add_u64 v[170:171], s[52:53], 0, v[250:251]
	v_cvt_pk_bf16_f32 v232, v145, v219
	v_mul_f32_e32 v141, v136, v141
	v_add_f32_e32 v143, v141, v141
	v_cvt_pk_bf16_f32 v233, v238, v233
	v_lshl_add_u64 v[170:171], v[170:171], 0, v[184:185]
	global_store_dwordx2 v[170:171], v[232:233], off
	v_cmp_nlt_f32_e32 vcc, s4, v143
	v_mul_f32_e32 v252, 0x3fb8aa3b, v143
	v_exp_f32_e32 v252, v252
	v_fmamk_f32 v145, v143, 0x3ab60b61, v237
	v_fmaak_f32 v145, v143, v145, 0x3d2aaaab
	v_fmaak_f32 v145, v143, v145, 0x3e2aaaab
	v_fma_f32 v145, v143, v145, 0.5
	v_fma_f32 v145, v143, v145, 1.0
	v_mul_f32_e32 v145, v143, v145
	v_add_f32_e32 v252, -1.0, v252
	v_cndmask_b32_e32 v145, v145, v252, vcc
	v_add_f32_e32 v143, v45, v133
	v_mul_f32_e32 v143, 0xbfb8aa3b, v143
	v_exp_f32_e32 v143, v143
	s_nop 0
	v_add_f32_e32 v143, 1.0, v143
	v_rcp_f32_e32 v143, v143
	s_nop 0
	v_mul_f32_e32 v143, v137, v143
	v_add_f32_e32 v147, v143, v143
	v_cmp_nlt_f32_e32 vcc, s4, v147
	v_mul_f32_e32 v252, 0x3fb8aa3b, v147
	v_exp_f32_e32 v252, v252
	v_fmamk_f32 v219, v147, 0x3ab60b61, v237
	v_fmaak_f32 v219, v147, v219, 0x3d2aaaab
	v_fmaak_f32 v219, v147, v219, 0x3e2aaaab
	v_fma_f32 v219, v147, v219, 0.5
	v_fma_f32 v219, v147, v219, 1.0
	v_mul_f32_e32 v219, v147, v219
	v_add_f32_e32 v252, -1.0, v252
	v_cndmask_b32_e32 v219, v219, v252, vcc
	v_add_f32_e32 v147, v46, v134
	v_mul_f32_e32 v147, 0xbfb8aa3b, v147
	v_exp_f32_e32 v147, v147
	s_nop 0
	v_add_f32_e32 v147, 1.0, v147
	v_rcp_f32_e32 v147, v147
	s_nop 0
	v_mul_f32_e32 v147, v138, v147
	v_add_f32_e32 v232, v147, v147
	v_cmp_nlt_f32_e32 vcc, s4, v232
	v_mul_f32_e32 v252, 0x3fb8aa3b, v232
	v_exp_f32_e32 v252, v252
	v_fmamk_f32 v233, v232, 0x3ab60b61, v237
	v_fmaak_f32 v233, v232, v233, 0x3d2aaaab
	v_fmaak_f32 v233, v232, v233, 0x3e2aaaab
	v_fma_f32 v233, v232, v233, 0.5
	v_fma_f32 v233, v232, v233, 1.0
	v_mul_f32_e32 v249, v232, v233
	v_add_f32_e32 v252, -1.0, v252
	v_cndmask_b32_e32 v249, v249, v252, vcc
	v_add_f32_e32 v232, v47, v135
	v_mul_f32_e32 v232, 0xbfb8aa3b, v232
	v_exp_f32_e32 v232, v232
	s_nop 0
	v_add_f32_e32 v232, 1.0, v232
	v_rcp_f32_e32 v232, v232
	s_nop 0
	v_mul_f32_e32 v232, v139, v232
	v_add_f32_e32 v250, v232, v232
	v_cmp_nlt_f32_e32 vcc, s4, v250
	v_mul_f32_e32 v252, 0x3fb8aa3b, v250
	v_exp_f32_e32 v252, v252
	v_fmamk_f32 v233, v250, 0x3ab60b61, v237
	v_fmaak_f32 v233, v250, v233, 0x3d2aaaab
	v_fmaak_f32 v233, v250, v233, 0x3e2aaaab
	v_fma_f32 v233, v250, v233, 0.5
	v_fma_f32 v233, v250, v233, 1.0
	v_mul_f32_e32 v233, v250, v233
	v_add_f32_e32 v252, -1.0, v252
	v_cndmask_b32_e32 v233, v233, v252, vcc
	v_add_f32_e32 v238, v42, v130
	v_add_f32_e32 v241, v40, v128
	v_mul_f32_e32 v238, 0xbfb8aa3b, v238
	v_mul_f32_e32 v241, 0xbfb8aa3b, v241
	v_exp_f32_e32 v238, v238
	v_exp_f32_e32 v241, v241
	v_max_f32_e64 v240, -v249, -v249
	v_max_f32_e64 v145, -v145, -v145
	v_add_f32_e32 v238, 1.0, v238
	v_max_f32_e32 v240, 0, v240
	v_add_f32_e32 v241, 1.0, v241
	v_max_f32_e32 v145, 0, v145
	v_rcp_f32_e32 v238, v238
	v_sqrt_f32_e32 v240, v240
	v_rcp_f32_e32 v241, v241
	v_sqrt_f32_e32 v145, v145
	v_max_f32_e64 v219, -v219, -v219
	v_mul_f32_e32 v238, v238, v240
	s_waitcnt vmcnt(4)
; __device__ __forceinline__ unsigned cvt_pk_bf16(float lo, float hi) { const f32x2_t v = {lo, hi}; const bf16x2_t b = __builtin_convertvector(v, bf16x2_t); return __builtin_bit_cast(unsigned, b); }
; __device__ __forceinline__ float lo_bf(unsigned w) { return __uint_as_float(w << 16); }
; __device__ __forceinline__ float hi_bf(unsigned w) { return __uint_as_float(w & 0xffff0000u); }
; __device__ __forceinline__ float sigmoidf_(float x) { return __builtin_amdgcn_rcpf(1.0f + __builtin_amdgcn_exp2f(-1.4426950408889634f * x)); }
;     __device__ __forceinline__ void operator()(AccRef acc, const Unit& u, int wr, int wc, int fr, int fq) const {
;     ...
;                 for (int m = 0; m < 4; ++m) { const size_t row = (size_t)(row0 + ai * HALF + m * 16);
;                     const u32x2 xw = xwv[m];
;                     const float xv[4] = {lo_bf(xw.x), hi_bf(xw.x), lo_bf(xw.y), hi_bf(xw.y)};
;                     float la[4], uo[4];
; #pragma unroll
;                     for (int i = 0; i < 4; ++i) { const float r = sigmoidf_(acc[ai][bj][m][0][i] + vba[i]), gi = sigmoidf_(acc[ai][bj][m][1][i] + vbx[i]);
;                         const float l = cc[i] * r; la[i] = l; const float x2 = 2.0f * l;
;                         const float em1 = (x2 > -0.25f) ? x2 * (1.0f + x2 * (0.5f + x2 * (1.0f / 6.0f + x2 * (1.0f / 24.0f + x2 * (1.0f / 120.0f + x2 * (1.0f / 720.0f)))))) : (__expf(x2) - 1.0f);
;                         uo[i] = __builtin_amdgcn_sqrtf(fmaxf(-em1, 0.0f)) * gi * xv[i]; }
;                     u32x2 w0, w1; w0.x = cvt_pk_bf16(la[0], la[1]); w0.y = cvt_pk_bf16(la[2], la[3]); w1.x = cvt_pk_bf16(uo[0], uo[1]); w1.y = cvt_pk_bf16(uo[2], uo[3]);
;                     *(u32x2*)(loga + ((size_t)dir * MT + row) * 512 + ch) = w0; *(u32x2*)(uu + ((size_t)dir * MT + row) * 512 + ch) = w1; } } }
	v_lshlrev_b32_e32 v240, 16, v174
	v_mul_f32_e32 v145, v241, v145
	v_mul_f32_e32 v145, v145, v240
	v_add_f32_e32 v240, v41, v129
	v_mul_f32_e32 v240, 0xbfb8aa3b, v240
	v_exp_f32_e32 v240, v240
	v_lshlrev_b32_e32 v239, 16, v175
	v_max_f32_e32 v219, 0, v219
	v_mul_f32_e32 v238, v238, v239
	v_add_f32_e32 v240, 1.0, v240
	v_add_f32_e32 v239, v43, v131
	v_rcp_f32_e32 v240, v240
	v_sqrt_f32_e32 v219, v219
	v_mul_f32_e32 v239, 0xbfb8aa3b, v239
	v_exp_f32_e32 v239, v239
	v_and_b32_e32 v174, 0xffff0000, v174
	v_mul_f32_e32 v219, v240, v219
	v_mul_f32_e32 v219, v219, v174
	v_and_b32_e32 v174, 0xffff0000, v175
	v_max_f32_e64 v175, -v233, -v233
	v_add_f32_e32 v239, 1.0, v239
	v_max_f32_e32 v175, 0, v175
	v_rcp_f32_e32 v239, v239
	v_sqrt_f32_e32 v175, v175
	v_lshlrev_b64 v[172:173], 9, v[172:173]
	v_lshl_add_u64 v[172:173], v[172:173], 0, s[22:23]
	v_lshlrev_b64 v[250:251], 1, v[172:173]
	v_mul_f32_e32 v175, v239, v175
	v_mul_f32_e32 v233, v175, v174
	v_cvt_pk_bf16_f32 v174, v141, v143
	v_add_f32_e32 v141, v28, v132
	v_mul_f32_e32 v141, 0xbfb8aa3b, v141
	v_exp_f32_e32 v141, v141
	v_lshl_add_u64 v[172:173], s[44:45], 0, v[250:251]
	v_cvt_pk_bf16_f32 v175, v147, v232
	v_lshl_add_u64 v[172:173], v[172:173], 0, v[184:185]
	v_add_f32_e32 v141, 1.0, v141
	v_rcp_f32_e32 v141, v141
	global_store_dwordx2 v[172:173], v[174:175], off
	v_lshl_add_u64 v[174:175], s[52:53], 0, v[250:251]
	v_cvt_pk_bf16_f32 v232, v145, v219
	v_mul_f32_e32 v141, v136, v141
	v_add_f32_e32 v143, v141, v141
	v_cvt_pk_bf16_f32 v233, v238, v233
	v_lshl_add_u64 v[174:175], v[174:175], 0, v[184:185]
	global_store_dwordx2 v[174:175], v[232:233], off
	v_cmp_nlt_f32_e32 vcc, s4, v143
	v_mul_f32_e32 v252, 0x3fb8aa3b, v143
	v_exp_f32_e32 v252, v252
	v_fmamk_f32 v145, v143, 0x3ab60b61, v237
	v_fmaak_f32 v145, v143, v145, 0x3d2aaaab
	v_fmaak_f32 v145, v143, v145, 0x3e2aaaab
	v_fma_f32 v145, v143, v145, 0.5
	v_fma_f32 v145, v143, v145, 1.0
	v_mul_f32_e32 v145, v143, v145
	v_add_f32_e32 v252, -1.0, v252
	v_cndmask_b32_e32 v145, v145, v252, vcc
	v_add_f32_e32 v143, v29, v133
	v_mul_f32_e32 v143, 0xbfb8aa3b, v143
	v_exp_f32_e32 v143, v143
	s_nop 0
	v_add_f32_e32 v143, 1.0, v143
	v_rcp_f32_e32 v143, v143
	s_nop 0
	v_mul_f32_e32 v143, v137, v143
	v_add_f32_e32 v147, v143, v143
	v_cmp_nlt_f32_e32 vcc, s4, v147
	v_mul_f32_e32 v252, 0x3fb8aa3b, v147
	v_exp_f32_e32 v252, v252
	v_fmamk_f32 v219, v147, 0x3ab60b61, v237
	v_fmaak_f32 v219, v147, v219, 0x3d2aaaab
	v_fmaak_f32 v219, v147, v219, 0x3e2aaaab
	v_fma_f32 v219, v147, v219, 0.5
	v_fma_f32 v219, v147, v219, 1.0
	v_mul_f32_e32 v219, v147, v219
	v_add_f32_e32 v252, -1.0, v252
	v_cndmask_b32_e32 v219, v219, v252, vcc
	v_add_f32_e32 v147, v30, v134
	v_mul_f32_e32 v147, 0xbfb8aa3b, v147
	v_exp_f32_e32 v147, v147
	s_nop 0
	v_add_f32_e32 v147, 1.0, v147
	v_rcp_f32_e32 v147, v147
	s_nop 0
	v_mul_f32_e32 v147, v138, v147
	v_add_f32_e32 v232, v147, v147
	v_cmp_nlt_f32_e32 vcc, s4, v232
	v_mul_f32_e32 v252, 0x3fb8aa3b, v232
	v_exp_f32_e32 v252, v252
	v_fmamk_f32 v233, v232, 0x3ab60b61, v237
	v_fmaak_f32 v233, v232, v233, 0x3d2aaaab
	v_fmaak_f32 v233, v232, v233, 0x3e2aaaab
	v_fma_f32 v233, v232, v233, 0.5
	v_fma_f32 v233, v232, v233, 1.0
	v_mul_f32_e32 v249, v232, v233
	v_add_f32_e32 v252, -1.0, v252
	v_cndmask_b32_e32 v249, v249, v252, vcc
	v_add_f32_e32 v232, v31, v135
	v_mul_f32_e32 v232, 0xbfb8aa3b, v232
	v_exp_f32_e32 v232, v232
	s_nop 0
	v_add_f32_e32 v232, 1.0, v232
	v_rcp_f32_e32 v232, v232
	s_nop 0
	v_mul_f32_e32 v232, v139, v232
	v_add_f32_e32 v250, v232, v232
	v_cmp_nlt_f32_e32 vcc, s4, v250
	v_mul_f32_e32 v252, 0x3fb8aa3b, v250
	v_exp_f32_e32 v252, v252
	v_fmamk_f32 v233, v250, 0x3ab60b61, v237
	v_fmaak_f32 v233, v250, v233, 0x3d2aaaab
	v_fmaak_f32 v233, v250, v233, 0x3e2aaaab
	v_fma_f32 v233, v250, v233, 0.5
	v_fma_f32 v233, v250, v233, 1.0
	v_mul_f32_e32 v233, v250, v233
	v_add_f32_e32 v252, -1.0, v252
	v_cndmask_b32_e32 v233, v233, v252, vcc
	v_add_f32_e32 v238, v26, v130
	v_add_f32_e32 v241, v24, v128
	v_mul_f32_e32 v238, 0xbfb8aa3b, v238
	v_mul_f32_e32 v241, 0xbfb8aa3b, v241
	v_exp_f32_e32 v238, v238
	v_exp_f32_e32 v241, v241
	v_max_f32_e64 v240, -v249, -v249
	v_max_f32_e64 v145, -v145, -v145
	v_add_f32_e32 v238, 1.0, v238
	v_max_f32_e32 v240, 0, v240
	v_add_f32_e32 v241, 1.0, v241
	v_max_f32_e32 v145, 0, v145
	v_rcp_f32_e32 v238, v238
	v_sqrt_f32_e32 v240, v240
	v_rcp_f32_e32 v241, v241
	v_sqrt_f32_e32 v145, v145
	v_max_f32_e64 v219, -v219, -v219
	v_mul_f32_e32 v238, v238, v240
	s_waitcnt vmcnt(5)
; __device__ __forceinline__ unsigned cvt_pk_bf16(float lo, float hi) { const f32x2_t v = {lo, hi}; const bf16x2_t b = __builtin_convertvector(v, bf16x2_t); return __builtin_bit_cast(unsigned, b); }
; __device__ __forceinline__ float lo_bf(unsigned w) { return __uint_as_float(w << 16); }
; __device__ __forceinline__ float hi_bf(unsigned w) { return __uint_as_float(w & 0xffff0000u); }
; __device__ __forceinline__ float sigmoidf_(float x) { return __builtin_amdgcn_rcpf(1.0f + __builtin_amdgcn_exp2f(-1.4426950408889634f * x)); }
;     __device__ __forceinline__ void operator()(AccRef acc, const Unit& u, int wr, int wc, int fr, int fq) const {
;     ...
;         for (int bj = 0; bj < 2; ++bj) { const int c = u.pn * BM + bj * HALF + wc * 32; const int dir = c >> 10; const int ch = ((c & 1023) >> 1) + 4 * fq;
;             const f32x4 vba = *(const f32x4*)(ba + dir * 512 + ch), vbx = *(const f32x4*)(bx + dir * 512 + ch), vl = *(const f32x4*)(lam + dir * 512 + ch);
;             const f32x4 cc = vl;
; #pragma unroll
;             for (int ai = 0; ai < 2; ++ai) {
;                 u32x2 xwv[4];
; #pragma unroll
;                 for (int m = 0; m < 4; ++m) xwv[m] = *(const u32x2*)(xc + (size_t)(row0 + ai * HALF + m * 16) * 512 + ch);
;     ...
;                 for (int m = 0; m < 4; ++m) { const size_t row = (size_t)(row0 + ai * HALF + m * 16);
;                     const u32x2 xw = xwv[m];
;                     const float xv[4] = {lo_bf(xw.x), hi_bf(xw.x), lo_bf(xw.y), hi_bf(xw.y)};
;                     float la[4], uo[4];
; #pragma unroll
;                     for (int i = 0; i < 4; ++i) { const float r = sigmoidf_(acc[ai][bj][m][0][i] + vba[i]), gi = sigmoidf_(acc[ai][bj][m][1][i] + vbx[i]);
;                         const float l = cc[i] * r; la[i] = l; const float x2 = 2.0f * l;
;                         const float em1 = (x2 > -0.25f) ? x2 * (1.0f + x2 * (0.5f + x2 * (1.0f / 6.0f + x2 * (1.0f / 24.0f + x2 * (1.0f / 120.0f + x2 * (1.0f / 720.0f)))))) : (__expf(x2) - 1.0f);
;                         uo[i] = __builtin_amdgcn_sqrtf(fmaxf(-em1, 0.0f)) * gi * xv[i]; }
;                     u32x2 w0, w1; w0.x = cvt_pk_bf16(la[0], la[1]); w0.y = cvt_pk_bf16(la[2], la[3]); w1.x = cvt_pk_bf16(uo[0], uo[1]); w1.y = cvt_pk_bf16(uo[2], uo[3]);
;                     *(u32x2*)(loga + ((size_t)dir * MT + row) * 512 + ch) = w0; *(u32x2*)(uu + ((size_t)dir * MT + row) * 512 + ch) = w1; } } }
	v_lshlrev_b32_e32 v240, 16, v178
	v_mul_f32_e32 v145, v241, v145
	v_mul_f32_e32 v145, v145, v240
	v_add_f32_e32 v240, v25, v129
	v_mul_f32_e32 v240, 0xbfb8aa3b, v240
	v_exp_f32_e32 v240, v240
	v_lshlrev_b32_e32 v239, 16, v179
	v_max_f32_e32 v219, 0, v219
	v_mul_f32_e32 v238, v238, v239
	v_add_f32_e32 v240, 1.0, v240
	v_add_f32_e32 v239, v27, v131
	v_rcp_f32_e32 v240, v240
	v_sqrt_f32_e32 v219, v219
	v_mul_f32_e32 v239, 0xbfb8aa3b, v239
	v_add_f32_e32 v132, v12, v132
	v_exp_f32_e32 v239, v239
	v_mul_f32_e32 v132, 0xbfb8aa3b, v132
	v_exp_f32_e32 v132, v132
	v_and_b32_e32 v178, 0xffff0000, v178
	v_mul_f32_e32 v219, v240, v219
	v_mul_f32_e32 v219, v219, v178
	v_and_b32_e32 v178, 0xffff0000, v179
	v_max_f32_e64 v179, -v233, -v233
	v_add_f32_e32 v239, 1.0, v239
	v_max_f32_e32 v179, 0, v179
	v_rcp_f32_e32 v239, v239
	v_sqrt_f32_e32 v179, v179
	v_add_f32_e32 v132, 1.0, v132
	v_lshlrev_b64 v[176:177], 9, v[176:177]
	v_rcp_f32_e32 v132, v132
	v_lshl_add_u64 v[176:177], v[176:177], 0, s[22:23]
	v_lshlrev_b64 v[250:251], 1, v[176:177]
	v_mul_f32_e32 v179, v239, v179
	v_lshl_add_u64 v[176:177], s[44:45], 0, v[250:251]
	v_mul_f32_e32 v233, v179, v178
	v_cvt_pk_bf16_f32 v178, v141, v143
	v_cvt_pk_bf16_f32 v179, v147, v232
	v_lshl_add_u64 v[176:177], v[176:177], 0, v[184:185]
	v_mul_f32_e32 v132, v136, v132
	global_store_dwordx2 v[176:177], v[178:179], off
	v_lshl_add_u64 v[178:179], s[52:53], 0, v[250:251]
	v_add_f32_e32 v141, v132, v132
	v_cvt_pk_bf16_f32 v232, v145, v219
	v_cvt_pk_bf16_f32 v233, v238, v233
	v_lshl_add_u64 v[178:179], v[178:179], 0, v[184:185]
	global_store_dwordx2 v[178:179], v[232:233], off
	v_cmp_nlt_f32_e32 vcc, s4, v141
	v_mul_f32_e32 v252, 0x3fb8aa3b, v141
	v_exp_f32_e32 v252, v252
	v_fmamk_f32 v136, v141, 0x3ab60b61, v237
	v_fmaak_f32 v136, v141, v136, 0x3d2aaaab
	v_fmaak_f32 v136, v141, v136, 0x3e2aaaab
	v_fma_f32 v136, v141, v136, 0.5
	v_fma_f32 v136, v141, v136, 1.0
	v_mul_f32_e32 v136, v141, v136
	v_add_f32_e32 v252, -1.0, v252
	v_cndmask_b32_e32 v136, v136, v252, vcc
	v_add_f32_e32 v133, v13, v133
	v_mul_f32_e32 v133, 0xbfb8aa3b, v133
	v_exp_f32_e32 v133, v133
	s_nop 0
	v_add_f32_e32 v133, 1.0, v133
	v_rcp_f32_e32 v133, v133
	s_nop 0
	v_mul_f32_e32 v133, v137, v133
	v_add_f32_e32 v141, v133, v133
	v_cmp_nlt_f32_e32 vcc, s4, v141
	v_mul_f32_e32 v252, 0x3fb8aa3b, v141
	v_exp_f32_e32 v252, v252
	v_fmamk_f32 v137, v141, 0x3ab60b61, v237
	v_fmaak_f32 v137, v141, v137, 0x3d2aaaab
	v_fmaak_f32 v137, v141, v137, 0x3e2aaaab
	v_fma_f32 v137, v141, v137, 0.5
	v_fma_f32 v137, v141, v137, 1.0
	v_mul_f32_e32 v137, v141, v137
	v_add_f32_e32 v252, -1.0, v252
	v_cndmask_b32_e32 v137, v137, v252, vcc
	v_add_f32_e32 v134, v14, v134
	v_mul_f32_e32 v134, 0xbfb8aa3b, v134
	v_exp_f32_e32 v134, v134
	s_nop 0
	v_add_f32_e32 v134, 1.0, v134
	v_rcp_f32_e32 v134, v134
	s_nop 0
	v_mul_f32_e32 v134, v138, v134
	v_add_f32_e32 v138, v134, v134
	v_cmp_nlt_f32_e32 vcc, s4, v138
	v_mul_f32_e32 v252, 0x3fb8aa3b, v138
	v_exp_f32_e32 v252, v252
	v_fmamk_f32 v141, v138, 0x3ab60b61, v237
	v_fmaak_f32 v141, v138, v141, 0x3d2aaaab
	v_fmaak_f32 v141, v138, v141, 0x3e2aaaab
	v_fma_f32 v141, v138, v141, 0.5
	v_fma_f32 v141, v138, v141, 1.0
	v_mul_f32_e32 v141, v138, v141
	v_add_f32_e32 v252, -1.0, v252
	v_cndmask_b32_e32 v141, v141, v252, vcc
	v_add_f32_e32 v135, v15, v135
	v_mul_f32_e32 v135, 0xbfb8aa3b, v135
	v_exp_f32_e32 v135, v135
	s_nop 0
	v_add_f32_e32 v135, 1.0, v135
	v_rcp_f32_e32 v135, v135
	s_nop 0
	v_mul_f32_e32 v135, v139, v135
	v_add_f32_e32 v139, v135, v135
	v_cmp_nlt_f32_e32 vcc, s4, v139
	v_mul_f32_e32 v252, 0x3fb8aa3b, v139
	v_exp_f32_e32 v252, v252
	v_fmamk_f32 v138, v139, 0x3ab60b61, v237
	v_fmaak_f32 v138, v139, v138, 0x3d2aaaab
	v_fmaak_f32 v138, v139, v138, 0x3e2aaaab
	v_fma_f32 v138, v139, v138, 0.5
	v_fma_f32 v138, v139, v138, 1.0
	v_mul_f32_e32 v138, v139, v138
	v_add_f32_e32 v252, -1.0, v252
	v_cndmask_b32_e32 v138, v138, v252, vcc
	v_add_f32_e32 v130, v10, v130
	v_mul_f32_e32 v130, 0xbfb8aa3b, v130
	v_exp_f32_e32 v130, v130
	v_max_f32_e64 v139, -v141, -v141
	v_max_f32_e32 v139, 0, v139
	v_add_f32_e32 v131, v11, v131
	v_add_f32_e32 v130, 1.0, v130
	v_sqrt_f32_e32 v139, v139
	v_rcp_f32_e32 v130, v130
	v_mul_f32_e32 v131, 0xbfb8aa3b, v131
	v_add_f32_e32 v128, v8, v128
	v_exp_f32_e32 v131, v131
	v_mul_f32_e32 v128, 0xbfb8aa3b, v128
	v_exp_f32_e32 v128, v128
	s_waitcnt vmcnt(6)
	v_lshlrev_b32_e32 v141, 16, v221
	v_mul_f32_e32 v130, v130, v139
	v_mul_f32_e32 v139, v130, v141
	v_add_f32_e32 v130, 1.0, v131
	v_max_f32_e64 v131, -v136, -v136
	v_add_f32_e32 v128, 1.0, v128
	v_max_f32_e32 v131, 0, v131
	v_rcp_f32_e32 v128, v128
	v_sqrt_f32_e32 v131, v131
	v_add_f32_e32 v129, v9, v129
	v_mul_f32_e32 v129, 0xbfb8aa3b, v129
	v_exp_f32_e32 v129, v129
	v_lshlrev_b32_e32 v136, 16, v220
	v_mul_f32_e32 v128, v128, v131
	v_mul_f32_e32 v131, v128, v136
	v_max_f32_e64 v136, -v137, -v137
	v_add_f32_e32 v128, 1.0, v129
	v_max_f32_e32 v136, 0, v136
	v_max_f32_e64 v137, -v138, -v138
	v_rcp_f32_e32 v128, v128
	v_sqrt_f32_e32 v136, v136
	v_max_f32_e32 v137, 0, v137
	v_rcp_f32_e32 v130, v130
	v_sqrt_f32_e32 v137, v137
	v_and_b32_e32 v129, 0xffff0000, v220
	v_mul_f32_e32 v128, v128, v136
	v_mul_f32_e32 v136, v128, v129
	v_and_b32_e32 v128, 0xffff0000, v221
	v_mul_f32_e32 v129, v130, v137
	v_mul_f32_e32 v137, v129, v128
	v_cvt_pk_bf16_f32 v128, v132, v133
	v_lshlrev_b64 v[132:133], 9, v[180:181]
	v_lshl_add_u64 v[132:133], v[132:133], 0, s[22:23]
	v_lshlrev_b64 v[132:133], 1, v[132:133]
	v_cvt_pk_bf16_f32 v129, v134, v135
	v_lshl_add_u64 v[134:135], s[44:45], 0, v[132:133]
	v_lshl_add_u64 v[180:181], v[134:135], 0, v[184:185]
	global_store_dwordx2 v[180:181], v[128:129], off
	v_lshl_add_u64 v[128:129], s[52:53], 0, v[132:133]
	v_mov_b32_e32 v147, v185
	v_cvt_pk_bf16_f32 v130, v131, v136
	v_cvt_pk_bf16_f32 v131, v139, v137
	v_lshl_add_u64 v[220:221], v[128:129], 0, v[184:185]
	v_lshl_add_u64 v[232:233], s[46:47], 0, v[146:147]
	global_store_dwordx2 v[220:221], v[130:131], off
	global_load_dwordx4 v[136:139], v[232:233], off offset:256
	v_lshl_add_u64 v[128:129], s[6:7], 0, v[146:147]
	v_lshl_add_u64 v[132:133], s[78:79], 0, v[146:147]
	global_load_dwordx4 v[128:131], v[128:129], off offset:256
	s_nop 0
	global_load_dwordx4 v[132:135], v[132:133], off offset:256
	s_nop 0
	global_load_dwordx2 v[232:233], v[150:151], off offset:128
	s_nop 0
	global_load_dwordx2 v[154:155], v[154:155], off offset:128
	s_nop 0
	global_load_dwordx2 v[150:151], v[158:159], off offset:128
	global_load_dwordx2 v[146:147], v[162:163], off offset:128
	s_waitcnt vmcnt(6)
; __device__ __forceinline__ unsigned cvt_pk_bf16(float lo, float hi) { const f32x2_t v = {lo, hi}; const bf16x2_t b = __builtin_convertvector(v, bf16x2_t); return __builtin_bit_cast(unsigned, b); }
; __device__ __forceinline__ float lo_bf(unsigned w) { return __uint_as_float(w << 16); }
; __device__ __forceinline__ float hi_bf(unsigned w) { return __uint_as_float(w & 0xffff0000u); }
; __device__ __forceinline__ float sigmoidf_(float x) { return __builtin_amdgcn_rcpf(1.0f + __builtin_amdgcn_exp2f(-1.4426950408889634f * x)); }
;     __device__ __forceinline__ void operator()(AccRef acc, const Unit& u, int wr, int wc, int fr, int fq) const {
;     ...
;                 for (int m = 0; m < 4; ++m) { const size_t row = (size_t)(row0 + ai * HALF + m * 16);
;                     const u32x2 xw = xwv[m];
;                     const float xv[4] = {lo_bf(xw.x), hi_bf(xw.x), lo_bf(xw.y), hi_bf(xw.y)};
;                     float la[4], uo[4];
; #pragma unroll
;                     for (int i = 0; i < 4; ++i) { const float r = sigmoidf_(acc[ai][bj][m][0][i] + vba[i]), gi = sigmoidf_(acc[ai][bj][m][1][i] + vbx[i]);
;                         const float l = cc[i] * r; la[i] = l; const float x2 = 2.0f * l;
;                         const float em1 = (x2 > -0.25f) ? x2 * (1.0f + x2 * (0.5f + x2 * (1.0f / 6.0f + x2 * (1.0f / 24.0f + x2 * (1.0f / 120.0f + x2 * (1.0f / 720.0f)))))) : (__expf(x2) - 1.0f);
;                         uo[i] = __builtin_amdgcn_sqrtf(fmaxf(-em1, 0.0f)) * gi * xv[i]; }
;                     u32x2 w0, w1; w0.x = cvt_pk_bf16(la[0], la[1]); w0.y = cvt_pk_bf16(la[2], la[3]); w1.x = cvt_pk_bf16(uo[0], uo[1]); w1.y = cvt_pk_bf16(uo[2], uo[3]);
;                     *(u32x2*)(loga + ((size_t)dir * MT + row) * 512 + ch) = w0; *(u32x2*)(uu + ((size_t)dir * MT + row) * 512 + ch) = w1; } } }
	v_add_f32_e32 v141, v116, v136
	v_mul_f32_e32 v141, 0xbfb8aa3b, v141
	v_exp_f32_e32 v141, v141
	s_nop 0
	v_add_f32_e32 v141, 1.0, v141
	v_rcp_f32_e32 v141, v141
	s_waitcnt vmcnt(4)
	v_mul_f32_e32 v141, v132, v141
	v_add_f32_e32 v143, v141, v141
	v_cmp_nlt_f32_e32 vcc, s4, v143
	v_mul_f32_e32 v252, 0x3fb8aa3b, v143
	v_exp_f32_e32 v252, v252
	v_fmamk_f32 v145, v143, 0x3ab60b61, v237
	v_fmaak_f32 v145, v143, v145, 0x3d2aaaab
	v_fmaak_f32 v145, v143, v145, 0x3e2aaaab
	v_fma_f32 v145, v143, v145, 0.5
	v_fma_f32 v145, v143, v145, 1.0
	v_mul_f32_e32 v145, v143, v145
	v_add_f32_e32 v252, -1.0, v252
	v_cndmask_b32_e32 v145, v145, v252, vcc
	v_add_f32_e32 v143, v117, v137
	v_mul_f32_e32 v143, 0xbfb8aa3b, v143
	v_exp_f32_e32 v143, v143
	s_nop 0
	v_add_f32_e32 v143, 1.0, v143
	v_rcp_f32_e32 v143, v143
	s_nop 0
	v_mul_f32_e32 v143, v133, v143
	v_add_f32_e32 v158, v143, v143
	v_cmp_nlt_f32_e32 vcc, s4, v158
	v_mul_f32_e32 v252, 0x3fb8aa3b, v158
	v_exp_f32_e32 v252, v252
	v_fmamk_f32 v159, v158, 0x3ab60b61, v237
	v_fmaak_f32 v159, v158, v159, 0x3d2aaaab
	v_fmaak_f32 v159, v158, v159, 0x3e2aaaab
	v_fma_f32 v159, v158, v159, 0.5
	v_fma_f32 v159, v158, v159, 1.0
	v_mul_f32_e32 v159, v158, v159
	v_add_f32_e32 v252, -1.0, v252
	v_cndmask_b32_e32 v159, v159, v252, vcc
	v_add_f32_e32 v158, v118, v138
	v_mul_f32_e32 v158, 0xbfb8aa3b, v158
	v_exp_f32_e32 v158, v158
	s_nop 0
	v_add_f32_e32 v158, 1.0, v158
	v_rcp_f32_e32 v158, v158
	s_nop 0
	v_mul_f32_e32 v158, v134, v158
	v_add_f32_e32 v162, v158, v158
	v_cmp_nlt_f32_e32 vcc, s4, v162
	v_mul_f32_e32 v252, 0x3fb8aa3b, v162
	v_exp_f32_e32 v252, v252
	v_fmamk_f32 v163, v162, 0x3ab60b61, v237
	v_fmaak_f32 v163, v162, v163, 0x3d2aaaab
	v_fmaak_f32 v163, v162, v163, 0x3e2aaaab
	v_fma_f32 v163, v162, v163, 0.5
	v_fma_f32 v163, v162, v163, 1.0
	v_mul_f32_e32 v184, v162, v163
	v_add_f32_e32 v252, -1.0, v252
	v_cndmask_b32_e32 v184, v184, v252, vcc
	v_add_f32_e32 v162, v119, v139
	v_mul_f32_e32 v162, 0xbfb8aa3b, v162
	v_exp_f32_e32 v162, v162
	s_nop 0
	v_add_f32_e32 v162, 1.0, v162
	v_rcp_f32_e32 v162, v162
	s_nop 0
	v_mul_f32_e32 v162, v135, v162
	v_add_f32_e32 v219, v162, v162
	v_cmp_nlt_f32_e32 vcc, s4, v219
	v_mul_f32_e32 v252, 0x3fb8aa3b, v219
	v_exp_f32_e32 v252, v252
	v_fmamk_f32 v163, v219, 0x3ab60b61, v237
	v_fmaak_f32 v163, v219, v163, 0x3d2aaaab
	v_fmaak_f32 v163, v219, v163, 0x3e2aaaab
	v_fma_f32 v163, v219, v163, 0.5
	v_fma_f32 v163, v219, v163, 1.0
	v_mul_f32_e32 v163, v219, v163
	v_add_f32_e32 v252, -1.0, v252
	v_cndmask_b32_e32 v163, v163, v252, vcc
	v_add_f32_e32 v219, v114, v130
	v_mul_f32_e32 v219, 0xbfb8aa3b, v219
	v_add_f32_e32 v239, v112, v128
	v_exp_f32_e32 v219, v219
	v_mul_f32_e32 v239, 0xbfb8aa3b, v239
	v_exp_f32_e32 v239, v239
	v_max_f32_e64 v184, -v184, -v184
	v_add_f32_e32 v219, 1.0, v219
	v_max_f32_e32 v184, 0, v184
	v_max_f32_e64 v145, -v145, -v145
	v_rcp_f32_e32 v219, v219
	v_sqrt_f32_e32 v184, v184
	v_add_f32_e32 v239, 1.0, v239
	v_max_f32_e32 v145, 0, v145
	v_rcp_f32_e32 v239, v239
	v_sqrt_f32_e32 v145, v145
	s_waitcnt vmcnt(3)
	v_lshlrev_b32_e32 v238, 16, v233
	v_mul_f32_e32 v184, v219, v184
	v_mul_f32_e32 v184, v184, v238
	v_lshlrev_b32_e32 v238, 16, v232
	v_mul_f32_e32 v145, v239, v145
	v_mul_f32_e32 v145, v145, v238
	v_add_f32_e32 v238, v113, v129
	v_add_f32_e32 v219, v115, v131
	v_mul_f32_e32 v238, 0xbfb8aa3b, v238
	v_mul_f32_e32 v219, 0xbfb8aa3b, v219
	v_exp_f32_e32 v238, v238
	v_exp_f32_e32 v219, v219
	v_max_f32_e64 v159, -v159, -v159
	v_max_f32_e32 v159, 0, v159
	v_add_f32_e32 v238, 1.0, v238
	v_max_f32_e64 v163, -v163, -v163
	v_add_f32_e32 v219, 1.0, v219
	v_rcp_f32_e32 v238, v238
	v_sqrt_f32_e32 v159, v159
	v_max_f32_e32 v163, 0, v163
	v_rcp_f32_e32 v219, v219
	v_sqrt_f32_e32 v163, v163
	v_and_b32_e32 v232, 0xffff0000, v232
	v_mul_f32_e32 v159, v238, v159
	v_mul_f32_e32 v159, v159, v232
	v_and_b32_e32 v232, 0xffff0000, v233
	v_mul_f32_e32 v163, v219, v163
	v_mul_f32_e32 v163, v163, v232
	v_cvt_pk_bf16_f32 v232, v141, v143
	v_add_f32_e32 v141, v100, v136
	v_mul_f32_e32 v141, 0xbfb8aa3b, v141
	v_exp_f32_e32 v141, v141
	v_cvt_pk_bf16_f32 v233, v158, v162
	v_cvt_pk_bf16_f32 v158, v145, v159
	v_cvt_pk_bf16_f32 v159, v184, v163
	v_add_f32_e32 v141, 1.0, v141
	v_rcp_f32_e32 v141, v141
	global_store_dwordx2 v[182:183], v[232:233], off offset:128
	global_store_dwordx2 v[222:223], v[158:159], off offset:128
	v_mul_f32_e32 v141, v132, v141
	v_add_f32_e32 v143, v141, v141
	v_cmp_nlt_f32_e32 vcc, s4, v143
	v_mul_f32_e32 v252, 0x3fb8aa3b, v143
	v_exp_f32_e32 v252, v252
	v_fmamk_f32 v145, v143, 0x3ab60b61, v237
	v_fmaak_f32 v145, v143, v145, 0x3d2aaaab
	v_fmaak_f32 v145, v143, v145, 0x3e2aaaab
	v_fma_f32 v145, v143, v145, 0.5
	v_fma_f32 v145, v143, v145, 1.0
	v_mul_f32_e32 v145, v143, v145
	v_add_f32_e32 v252, -1.0, v252
	v_cndmask_b32_e32 v145, v145, v252, vcc
	v_add_f32_e32 v143, v101, v137
	v_mul_f32_e32 v143, 0xbfb8aa3b, v143
	v_exp_f32_e32 v143, v143
	s_nop 0
	v_add_f32_e32 v143, 1.0, v143
	v_rcp_f32_e32 v143, v143
	s_nop 0
	v_mul_f32_e32 v143, v133, v143
	v_add_f32_e32 v158, v143, v143
	v_cmp_nlt_f32_e32 vcc, s4, v158
	v_mul_f32_e32 v252, 0x3fb8aa3b, v158
	v_exp_f32_e32 v252, v252
	v_fmamk_f32 v159, v158, 0x3ab60b61, v237
	v_fmaak_f32 v159, v158, v159, 0x3d2aaaab
	v_fmaak_f32 v159, v158, v159, 0x3e2aaaab
	v_fma_f32 v159, v158, v159, 0.5
	v_fma_f32 v159, v158, v159, 1.0
	v_mul_f32_e32 v159, v158, v159
	v_add_f32_e32 v252, -1.0, v252
	v_cndmask_b32_e32 v159, v159, v252, vcc
	v_add_f32_e32 v158, v102, v138
	v_mul_f32_e32 v158, 0xbfb8aa3b, v158
	v_exp_f32_e32 v158, v158
	s_nop 0
	v_add_f32_e32 v158, 1.0, v158
	v_rcp_f32_e32 v158, v158
	s_nop 0
	v_mul_f32_e32 v158, v134, v158
; __device__ __forceinline__ unsigned cvt_pk_bf16(float lo, float hi) { const f32x2_t v = {lo, hi}; const bf16x2_t b = __builtin_convertvector(v, bf16x2_t); return __builtin_bit_cast(unsigned, b); }
; __device__ __forceinline__ float lo_bf(unsigned w) { return __uint_as_float(w << 16); }
; __device__ __forceinline__ float hi_bf(unsigned w) { return __uint_as_float(w & 0xffff0000u); }
; __device__ __forceinline__ float sigmoidf_(float x) { return __builtin_amdgcn_rcpf(1.0f + __builtin_amdgcn_exp2f(-1.4426950408889634f * x)); }
;     __device__ __forceinline__ void operator()(AccRef acc, const Unit& u, int wr, int wc, int fr, int fq) const {
;     ...
;                 for (int m = 0; m < 4; ++m) { const size_t row = (size_t)(row0 + ai * HALF + m * 16);
;                     const u32x2 xw = xwv[m];
;                     const float xv[4] = {lo_bf(xw.x), hi_bf(xw.x), lo_bf(xw.y), hi_bf(xw.y)};
;                     float la[4], uo[4];
; #pragma unroll
;                     for (int i = 0; i < 4; ++i) { const float r = sigmoidf_(acc[ai][bj][m][0][i] + vba[i]), gi = sigmoidf_(acc[ai][bj][m][1][i] + vbx[i]);
;                         const float l = cc[i] * r; la[i] = l; const float x2 = 2.0f * l;
;                         const float em1 = (x2 > -0.25f) ? x2 * (1.0f + x2 * (0.5f + x2 * (1.0f / 6.0f + x2 * (1.0f / 24.0f + x2 * (1.0f / 120.0f + x2 * (1.0f / 720.0f)))))) : (__expf(x2) - 1.0f);
;                         uo[i] = __builtin_amdgcn_sqrtf(fmaxf(-em1, 0.0f)) * gi * xv[i]; }
;                     u32x2 w0, w1; w0.x = cvt_pk_bf16(la[0], la[1]); w0.y = cvt_pk_bf16(la[2], la[3]); w1.x = cvt_pk_bf16(uo[0], uo[1]); w1.y = cvt_pk_bf16(uo[2], uo[3]);
;                     *(u32x2*)(loga + ((size_t)dir * MT + row) * 512 + ch) = w0; *(u32x2*)(uu + ((size_t)dir * MT + row) * 512 + ch) = w1; } } }
	v_add_f32_e32 v162, v158, v158
	v_cmp_nlt_f32_e32 vcc, s4, v162
	v_mul_f32_e32 v252, 0x3fb8aa3b, v162
	v_exp_f32_e32 v252, v252
	v_fmamk_f32 v163, v162, 0x3ab60b61, v237
	v_fmaak_f32 v163, v162, v163, 0x3d2aaaab
	v_fmaak_f32 v163, v162, v163, 0x3e2aaaab
	v_fma_f32 v163, v162, v163, 0.5
	v_fma_f32 v163, v162, v163, 1.0
	v_mul_f32_e32 v182, v162, v163
	v_add_f32_e32 v252, -1.0, v252
	v_cndmask_b32_e32 v182, v182, v252, vcc
	v_add_f32_e32 v162, v103, v139
	v_mul_f32_e32 v162, 0xbfb8aa3b, v162
	v_exp_f32_e32 v162, v162
	s_nop 0
	v_add_f32_e32 v162, 1.0, v162
	v_rcp_f32_e32 v162, v162
	s_nop 0
	v_mul_f32_e32 v162, v135, v162
	v_add_f32_e32 v183, v162, v162
	v_cmp_nlt_f32_e32 vcc, s4, v183
	v_mul_f32_e32 v252, 0x3fb8aa3b, v183
	v_exp_f32_e32 v252, v252
	v_fmamk_f32 v163, v183, 0x3ab60b61, v237
	v_fmaak_f32 v163, v183, v163, 0x3d2aaaab
	v_fmaak_f32 v163, v183, v163, 0x3e2aaaab
	v_fma_f32 v163, v183, v163, 0.5
	v_fma_f32 v163, v183, v163, 1.0
	v_mul_f32_e32 v163, v183, v163
	v_add_f32_e32 v252, -1.0, v252
	v_cndmask_b32_e32 v163, v163, v252, vcc
	v_add_f32_e32 v183, v98, v130
	v_mul_f32_e32 v183, 0xbfb8aa3b, v183
	v_add_f32_e32 v219, v96, v128
	v_exp_f32_e32 v183, v183
	v_mul_f32_e32 v219, 0xbfb8aa3b, v219
	v_exp_f32_e32 v219, v219
	v_max_f32_e64 v182, -v182, -v182
	v_add_f32_e32 v183, 1.0, v183
	v_max_f32_e32 v182, 0, v182
	v_max_f32_e64 v145, -v145, -v145
	v_rcp_f32_e32 v183, v183
	v_sqrt_f32_e32 v182, v182
	v_add_f32_e32 v219, 1.0, v219
	v_max_f32_e32 v145, 0, v145
	v_rcp_f32_e32 v219, v219
	v_sqrt_f32_e32 v145, v145
	s_waitcnt vmcnt(4)
	v_lshlrev_b32_e32 v184, 16, v155
	v_mul_f32_e32 v182, v183, v182
	v_mul_f32_e32 v182, v182, v184
	v_lshlrev_b32_e32 v184, 16, v154
	v_mul_f32_e32 v145, v219, v145
	v_mul_f32_e32 v145, v145, v184
	v_add_f32_e32 v184, v97, v129
	v_mul_f32_e32 v184, 0xbfb8aa3b, v184
	v_exp_f32_e32 v184, v184
	v_max_f32_e64 v159, -v159, -v159
	v_max_f32_e32 v159, 0, v159
	v_add_f32_e32 v183, v99, v131
	v_add_f32_e32 v184, 1.0, v184
	v_rcp_f32_e32 v184, v184
	v_sqrt_f32_e32 v159, v159
	v_mul_f32_e32 v183, 0xbfb8aa3b, v183
	v_exp_f32_e32 v183, v183
	v_and_b32_e32 v154, 0xffff0000, v154
	v_mul_f32_e32 v159, v184, v159
	v_mul_f32_e32 v159, v159, v154
	v_and_b32_e32 v154, 0xffff0000, v155
	v_max_f32_e64 v155, -v163, -v163
	v_add_f32_e32 v183, 1.0, v183
	v_max_f32_e32 v155, 0, v155
	v_rcp_f32_e32 v183, v183
	v_sqrt_f32_e32 v155, v155
	s_nop 0
	v_mul_f32_e32 v155, v183, v155
	v_mul_f32_e32 v163, v155, v154
	v_cvt_pk_bf16_f32 v154, v141, v143
	v_add_f32_e32 v141, v84, v136
	v_mul_f32_e32 v141, 0xbfb8aa3b, v141
	v_exp_f32_e32 v141, v141
	v_cvt_pk_bf16_f32 v155, v158, v162
	v_cvt_pk_bf16_f32 v158, v145, v159
	v_cvt_pk_bf16_f32 v159, v182, v163
	v_add_f32_e32 v141, 1.0, v141
	v_rcp_f32_e32 v141, v141
	global_store_dwordx2 v[224:225], v[154:155], off offset:128
	global_store_dwordx2 v[226:227], v[158:159], off offset:128
	v_mul_f32_e32 v141, v132, v141
	v_add_f32_e32 v143, v141, v141
	v_cmp_nlt_f32_e32 vcc, s4, v143
	v_mul_f32_e32 v252, 0x3fb8aa3b, v143
	v_exp_f32_e32 v252, v252
	v_fmamk_f32 v145, v143, 0x3ab60b61, v237
	v_fmaak_f32 v145, v143, v145, 0x3d2aaaab
	v_fmaak_f32 v145, v143, v145, 0x3e2aaaab
	v_fma_f32 v145, v143, v145, 0.5
	v_fma_f32 v145, v143, v145, 1.0
	v_mul_f32_e32 v145, v143, v145
	v_add_f32_e32 v252, -1.0, v252
	v_cndmask_b32_e32 v145, v145, v252, vcc
	v_add_f32_e32 v143, v85, v137
	v_mul_f32_e32 v143, 0xbfb8aa3b, v143
	v_exp_f32_e32 v143, v143
	s_nop 0
	v_add_f32_e32 v143, 1.0, v143
	v_rcp_f32_e32 v143, v143
	s_nop 0
	v_mul_f32_e32 v143, v133, v143
	v_add_f32_e32 v154, v143, v143
	v_cmp_nlt_f32_e32 vcc, s4, v154
	v_mul_f32_e32 v252, 0x3fb8aa3b, v154
	v_exp_f32_e32 v252, v252
	v_fmamk_f32 v155, v154, 0x3ab60b61, v237
	v_fmaak_f32 v155, v154, v155, 0x3d2aaaab
	v_fmaak_f32 v155, v154, v155, 0x3e2aaaab
	v_fma_f32 v155, v154, v155, 0.5
	v_fma_f32 v155, v154, v155, 1.0
	v_mul_f32_e32 v155, v154, v155
	v_add_f32_e32 v252, -1.0, v252
	v_cndmask_b32_e32 v155, v155, v252, vcc
	v_add_f32_e32 v154, v86, v138
	v_mul_f32_e32 v154, 0xbfb8aa3b, v154
	v_exp_f32_e32 v154, v154
	s_nop 0
	v_add_f32_e32 v154, 1.0, v154
	v_rcp_f32_e32 v154, v154
	s_nop 0
	v_mul_f32_e32 v154, v134, v154
	v_add_f32_e32 v158, v154, v154
	v_cmp_nlt_f32_e32 vcc, s4, v158
	v_mul_f32_e32 v252, 0x3fb8aa3b, v158
	v_exp_f32_e32 v252, v252
	v_fmamk_f32 v159, v158, 0x3ab60b61, v237
	v_fmaak_f32 v159, v158, v159, 0x3d2aaaab
	v_fmaak_f32 v159, v158, v159, 0x3e2aaaab
	v_fma_f32 v159, v158, v159, 0.5
	v_fma_f32 v159, v158, v159, 1.0
	v_mul_f32_e32 v162, v158, v159
	v_add_f32_e32 v252, -1.0, v252
	v_cndmask_b32_e32 v162, v162, v252, vcc
	v_add_f32_e32 v158, v87, v139
	v_mul_f32_e32 v158, 0xbfb8aa3b, v158
	v_exp_f32_e32 v158, v158
	s_nop 0
	v_add_f32_e32 v158, 1.0, v158
	v_rcp_f32_e32 v158, v158
	s_nop 0
	v_mul_f32_e32 v158, v135, v158
	v_add_f32_e32 v163, v158, v158
	v_cmp_nlt_f32_e32 vcc, s4, v163
	v_mul_f32_e32 v252, 0x3fb8aa3b, v163
	v_exp_f32_e32 v252, v252
	v_fmamk_f32 v159, v163, 0x3ab60b61, v237
	v_fmaak_f32 v159, v163, v159, 0x3d2aaaab
	v_fmaak_f32 v159, v163, v159, 0x3e2aaaab
	v_fma_f32 v159, v163, v159, 0.5
	v_fma_f32 v159, v163, v159, 1.0
	v_mul_f32_e32 v159, v163, v159
	v_add_f32_e32 v252, -1.0, v252
	v_cndmask_b32_e32 v159, v159, v252, vcc
	v_add_f32_e32 v163, v82, v130
	v_mul_f32_e32 v163, 0xbfb8aa3b, v163
	v_add_f32_e32 v183, v80, v128
	v_exp_f32_e32 v163, v163
	v_mul_f32_e32 v183, 0xbfb8aa3b, v183
	v_exp_f32_e32 v183, v183
	v_max_f32_e64 v162, -v162, -v162
	v_add_f32_e32 v163, 1.0, v163
	v_max_f32_e32 v162, 0, v162
	v_max_f32_e64 v145, -v145, -v145
	v_rcp_f32_e32 v163, v163
	v_sqrt_f32_e32 v162, v162
	v_add_f32_e32 v183, 1.0, v183
	v_max_f32_e32 v145, 0, v145
	v_rcp_f32_e32 v183, v183
	v_sqrt_f32_e32 v145, v145
	s_waitcnt vmcnt(5)
; __device__ __forceinline__ unsigned cvt_pk_bf16(float lo, float hi) { const f32x2_t v = {lo, hi}; const bf16x2_t b = __builtin_convertvector(v, bf16x2_t); return __builtin_bit_cast(unsigned, b); }
; __device__ __forceinline__ float lo_bf(unsigned w) { return __uint_as_float(w << 16); }
; __device__ __forceinline__ float hi_bf(unsigned w) { return __uint_as_float(w & 0xffff0000u); }
; __device__ __forceinline__ float sigmoidf_(float x) { return __builtin_amdgcn_rcpf(1.0f + __builtin_amdgcn_exp2f(-1.4426950408889634f * x)); }
;     __device__ __forceinline__ void operator()(AccRef acc, const Unit& u, int wr, int wc, int fr, int fq) const {
;     ...
;                 for (int m = 0; m < 4; ++m) xwv[m] = *(const u32x2*)(xc + (size_t)(row0 + ai * HALF + m * 16) * 512 + ch);
;     ...
;                 for (int m = 0; m < 4; ++m) { const size_t row = (size_t)(row0 + ai * HALF + m * 16);
;                     const u32x2 xw = xwv[m];
;                     const float xv[4] = {lo_bf(xw.x), hi_bf(xw.x), lo_bf(xw.y), hi_bf(xw.y)};
;                     float la[4], uo[4];
; #pragma unroll
;                     for (int i = 0; i < 4; ++i) { const float r = sigmoidf_(acc[ai][bj][m][0][i] + vba[i]), gi = sigmoidf_(acc[ai][bj][m][1][i] + vbx[i]);
;                         const float l = cc[i] * r; la[i] = l; const float x2 = 2.0f * l;
;                         const float em1 = (x2 > -0.25f) ? x2 * (1.0f + x2 * (0.5f + x2 * (1.0f / 6.0f + x2 * (1.0f / 24.0f + x2 * (1.0f / 120.0f + x2 * (1.0f / 720.0f)))))) : (__expf(x2) - 1.0f);
;                         uo[i] = __builtin_amdgcn_sqrtf(fmaxf(-em1, 0.0f)) * gi * xv[i]; }
;                     u32x2 w0, w1; w0.x = cvt_pk_bf16(la[0], la[1]); w0.y = cvt_pk_bf16(la[2], la[3]); w1.x = cvt_pk_bf16(uo[0], uo[1]); w1.y = cvt_pk_bf16(uo[2], uo[3]);
;                     *(u32x2*)(loga + ((size_t)dir * MT + row) * 512 + ch) = w0; *(u32x2*)(uu + ((size_t)dir * MT + row) * 512 + ch) = w1; } } }
	v_lshlrev_b32_e32 v182, 16, v151
	v_mul_f32_e32 v162, v163, v162
	v_mul_f32_e32 v162, v162, v182
	v_lshlrev_b32_e32 v182, 16, v150
	v_mul_f32_e32 v145, v183, v145
	v_mul_f32_e32 v145, v145, v182
	v_add_f32_e32 v182, v81, v129
	v_mul_f32_e32 v182, 0xbfb8aa3b, v182
	v_exp_f32_e32 v182, v182
	v_max_f32_e64 v155, -v155, -v155
	v_max_f32_e32 v155, 0, v155
	v_add_f32_e32 v163, v83, v131
	v_add_f32_e32 v182, 1.0, v182
	v_rcp_f32_e32 v182, v182
	v_sqrt_f32_e32 v155, v155
	v_mul_f32_e32 v163, 0xbfb8aa3b, v163
	v_exp_f32_e32 v163, v163
	v_and_b32_e32 v150, 0xffff0000, v150
	v_mul_f32_e32 v155, v182, v155
	v_mul_f32_e32 v155, v155, v150
	v_and_b32_e32 v150, 0xffff0000, v151
	v_max_f32_e64 v151, -v159, -v159
	v_add_f32_e32 v163, 1.0, v163
	v_max_f32_e32 v151, 0, v151
	v_rcp_f32_e32 v163, v163
	v_sqrt_f32_e32 v151, v151
	s_nop 0
	v_mul_f32_e32 v151, v163, v151
	v_mul_f32_e32 v159, v151, v150
	v_cvt_pk_bf16_f32 v150, v141, v143
	v_add_f32_e32 v141, v68, v136
	v_mul_f32_e32 v141, 0xbfb8aa3b, v141
	v_exp_f32_e32 v141, v141
	v_cvt_pk_bf16_f32 v151, v154, v158
	v_cvt_pk_bf16_f32 v154, v145, v155
	v_cvt_pk_bf16_f32 v155, v162, v159
	v_add_f32_e32 v141, 1.0, v141
	v_rcp_f32_e32 v141, v141
	global_store_dwordx2 v[228:229], v[150:151], off offset:128
	global_store_dwordx2 v[230:231], v[154:155], off offset:128
	v_mul_f32_e32 v141, v132, v141
	v_add_f32_e32 v143, v141, v141
	v_cmp_nlt_f32_e32 vcc, s4, v143
	v_mul_f32_e32 v252, 0x3fb8aa3b, v143
	v_exp_f32_e32 v252, v252
	v_fmamk_f32 v145, v143, 0x3ab60b61, v237
	v_fmaak_f32 v145, v143, v145, 0x3d2aaaab
	v_fmaak_f32 v145, v143, v145, 0x3e2aaaab
	v_fma_f32 v145, v143, v145, 0.5
	v_fma_f32 v145, v143, v145, 1.0
	v_mul_f32_e32 v145, v143, v145
	v_add_f32_e32 v252, -1.0, v252
	v_cndmask_b32_e32 v145, v145, v252, vcc
	v_add_f32_e32 v143, v69, v137
	v_mul_f32_e32 v143, 0xbfb8aa3b, v143
	v_exp_f32_e32 v143, v143
	s_nop 0
	v_add_f32_e32 v143, 1.0, v143
	v_rcp_f32_e32 v143, v143
	s_nop 0
	v_mul_f32_e32 v143, v133, v143
	v_add_f32_e32 v150, v143, v143
	v_cmp_nlt_f32_e32 vcc, s4, v150
	v_mul_f32_e32 v252, 0x3fb8aa3b, v150
	v_exp_f32_e32 v252, v252
	v_fmamk_f32 v151, v150, 0x3ab60b61, v237
	v_fmaak_f32 v151, v150, v151, 0x3d2aaaab
	v_fmaak_f32 v151, v150, v151, 0x3e2aaaab
	v_fma_f32 v151, v150, v151, 0.5
	v_fma_f32 v151, v150, v151, 1.0
	v_mul_f32_e32 v151, v150, v151
	v_add_f32_e32 v252, -1.0, v252
	v_cndmask_b32_e32 v151, v151, v252, vcc
	v_add_f32_e32 v150, v70, v138
	v_mul_f32_e32 v150, 0xbfb8aa3b, v150
	v_exp_f32_e32 v150, v150
	s_nop 0
	v_add_f32_e32 v150, 1.0, v150
	v_rcp_f32_e32 v150, v150
	s_nop 0
	v_mul_f32_e32 v150, v134, v150
	v_add_f32_e32 v154, v150, v150
	v_cmp_nlt_f32_e32 vcc, s4, v154
	v_mul_f32_e32 v252, 0x3fb8aa3b, v154
	v_exp_f32_e32 v252, v252
	v_fmamk_f32 v155, v154, 0x3ab60b61, v237
	v_fmaak_f32 v155, v154, v155, 0x3d2aaaab
	v_fmaak_f32 v155, v154, v155, 0x3e2aaaab
	v_fma_f32 v155, v154, v155, 0.5
	v_fma_f32 v155, v154, v155, 1.0
	v_mul_f32_e32 v158, v154, v155
	v_add_f32_e32 v252, -1.0, v252
	v_cndmask_b32_e32 v158, v158, v252, vcc
	v_add_f32_e32 v154, v71, v139
	v_mul_f32_e32 v154, 0xbfb8aa3b, v154
	v_exp_f32_e32 v154, v154
	s_nop 0
	v_add_f32_e32 v154, 1.0, v154
	v_rcp_f32_e32 v154, v154
	s_nop 0
	v_mul_f32_e32 v154, v135, v154
	v_add_f32_e32 v159, v154, v154
	v_cmp_nlt_f32_e32 vcc, s4, v159
	v_mul_f32_e32 v252, 0x3fb8aa3b, v159
	v_exp_f32_e32 v252, v252
	v_fmamk_f32 v155, v159, 0x3ab60b61, v237
	v_fmaak_f32 v155, v159, v155, 0x3d2aaaab
	v_fmaak_f32 v155, v159, v155, 0x3e2aaaab
	v_fma_f32 v155, v159, v155, 0.5
	v_fma_f32 v155, v159, v155, 1.0
	v_mul_f32_e32 v155, v159, v155
	v_add_f32_e32 v252, -1.0, v252
	v_cndmask_b32_e32 v155, v155, v252, vcc
	v_add_f32_e32 v159, v66, v130
	v_mul_f32_e32 v159, 0xbfb8aa3b, v159
	v_add_f32_e32 v163, v64, v128
	v_exp_f32_e32 v159, v159
	v_mul_f32_e32 v163, 0xbfb8aa3b, v163
	v_exp_f32_e32 v163, v163
	v_max_f32_e64 v158, -v158, -v158
	v_add_f32_e32 v159, 1.0, v159
	v_max_f32_e32 v158, 0, v158
	v_max_f32_e64 v145, -v145, -v145
	v_rcp_f32_e32 v159, v159
	v_sqrt_f32_e32 v158, v158
	v_add_f32_e32 v163, 1.0, v163
	v_max_f32_e32 v145, 0, v145
	v_rcp_f32_e32 v163, v163
	v_sqrt_f32_e32 v145, v145
	s_waitcnt vmcnt(6)
	v_lshlrev_b32_e32 v162, 16, v147
	v_mul_f32_e32 v158, v159, v158
	v_mul_f32_e32 v158, v158, v162
	v_lshlrev_b32_e32 v162, 16, v146
	v_mul_f32_e32 v145, v163, v145
	v_mul_f32_e32 v145, v145, v162
	v_add_f32_e32 v162, v65, v129
	v_mul_f32_e32 v162, 0xbfb8aa3b, v162
	v_exp_f32_e32 v162, v162
	v_max_f32_e64 v151, -v151, -v151
	v_max_f32_e32 v151, 0, v151
	v_add_f32_e32 v159, v67, v131
	v_add_f32_e32 v162, 1.0, v162
	v_rcp_f32_e32 v162, v162
	v_sqrt_f32_e32 v151, v151
	v_mul_f32_e32 v159, 0xbfb8aa3b, v159
	v_exp_f32_e32 v159, v159
	v_and_b32_e32 v146, 0xffff0000, v146
	v_mul_f32_e32 v151, v162, v151
	v_mul_f32_e32 v151, v151, v146
	v_and_b32_e32 v146, 0xffff0000, v147
	v_max_f32_e64 v147, -v155, -v155
	v_add_f32_e32 v159, 1.0, v159
	v_max_f32_e32 v147, 0, v147
	v_rcp_f32_e32 v159, v159
	v_sqrt_f32_e32 v147, v147
	s_nop 0
	v_mul_f32_e32 v147, v159, v147
	v_mul_f32_e32 v155, v147, v146
	v_cvt_pk_bf16_f32 v146, v141, v143
	v_cvt_pk_bf16_f32 v147, v150, v154
	v_cvt_pk_bf16_f32 v150, v145, v151
	v_cvt_pk_bf16_f32 v151, v158, v155
	global_store_dwordx2 v[148:149], v[146:147], off offset:128
	global_store_dwordx2 v[152:153], v[150:151], off offset:128
	global_load_dwordx2 v[152:153], v[156:157], off offset:128
	s_nop 0
	global_load_dwordx2 v[150:151], v[160:161], off offset:128
	global_load_dwordx2 v[148:149], v[164:165], off offset:128
	global_load_dwordx2 v[146:147], v[166:167], off offset:128
	v_add_f32_e32 v141, v52, v136
	v_mul_f32_e32 v141, 0xbfb8aa3b, v141
; __device__ __forceinline__ unsigned cvt_pk_bf16(float lo, float hi) { const f32x2_t v = {lo, hi}; const bf16x2_t b = __builtin_convertvector(v, bf16x2_t); return __builtin_bit_cast(unsigned, b); }
; __device__ __forceinline__ float lo_bf(unsigned w) { return __uint_as_float(w << 16); }
; __device__ __forceinline__ float hi_bf(unsigned w) { return __uint_as_float(w & 0xffff0000u); }
; __device__ __forceinline__ float sigmoidf_(float x) { return __builtin_amdgcn_rcpf(1.0f + __builtin_amdgcn_exp2f(-1.4426950408889634f * x)); }
;     __device__ __forceinline__ void operator()(AccRef acc, const Unit& u, int wr, int wc, int fr, int fq) const {
;     ...
;                 for (int m = 0; m < 4; ++m) { const size_t row = (size_t)(row0 + ai * HALF + m * 16);
;                     const u32x2 xw = xwv[m];
;                     const float xv[4] = {lo_bf(xw.x), hi_bf(xw.x), lo_bf(xw.y), hi_bf(xw.y)};
;                     float la[4], uo[4];
; #pragma unroll
;                     for (int i = 0; i < 4; ++i) { const float r = sigmoidf_(acc[ai][bj][m][0][i] + vba[i]), gi = sigmoidf_(acc[ai][bj][m][1][i] + vbx[i]);
;                         const float l = cc[i] * r; la[i] = l; const float x2 = 2.0f * l;
;                         const float em1 = (x2 > -0.25f) ? x2 * (1.0f + x2 * (0.5f + x2 * (1.0f / 6.0f + x2 * (1.0f / 24.0f + x2 * (1.0f / 120.0f + x2 * (1.0f / 720.0f)))))) : (__expf(x2) - 1.0f);
;                         uo[i] = __builtin_amdgcn_sqrtf(fmaxf(-em1, 0.0f)) * gi * xv[i]; }
;                     u32x2 w0, w1; w0.x = cvt_pk_bf16(la[0], la[1]); w0.y = cvt_pk_bf16(la[2], la[3]); w1.x = cvt_pk_bf16(uo[0], uo[1]); w1.y = cvt_pk_bf16(uo[2], uo[3]);
;                     *(u32x2*)(loga + ((size_t)dir * MT + row) * 512 + ch) = w0; *(u32x2*)(uu + ((size_t)dir * MT + row) * 512 + ch) = w1; } } }
	v_exp_f32_e32 v141, v141
	s_nop 0
	v_add_f32_e32 v141, 1.0, v141
	v_rcp_f32_e32 v141, v141
	s_nop 0
	v_mul_f32_e32 v141, v132, v141
	v_add_f32_e32 v143, v141, v141
	v_cmp_nlt_f32_e32 vcc, s4, v143
	v_mul_f32_e32 v252, 0x3fb8aa3b, v143
	v_exp_f32_e32 v252, v252
	v_fmamk_f32 v145, v143, 0x3ab60b61, v237
	v_fmaak_f32 v145, v143, v145, 0x3d2aaaab
	v_fmaak_f32 v145, v143, v145, 0x3e2aaaab
	v_fma_f32 v145, v143, v145, 0.5
	v_fma_f32 v145, v143, v145, 1.0
	v_mul_f32_e32 v145, v143, v145
	v_add_f32_e32 v252, -1.0, v252
	v_cndmask_b32_e32 v145, v145, v252, vcc
	v_add_f32_e32 v143, v53, v137
	v_mul_f32_e32 v143, 0xbfb8aa3b, v143
	v_exp_f32_e32 v143, v143
	s_nop 0
	v_add_f32_e32 v143, 1.0, v143
	v_rcp_f32_e32 v143, v143
	s_nop 0
	v_mul_f32_e32 v143, v133, v143
	v_add_f32_e32 v154, v143, v143
	v_cmp_nlt_f32_e32 vcc, s4, v154
	v_mul_f32_e32 v252, 0x3fb8aa3b, v154
	v_exp_f32_e32 v252, v252
	v_fmamk_f32 v155, v154, 0x3ab60b61, v237
	v_fmaak_f32 v155, v154, v155, 0x3d2aaaab
	v_fmaak_f32 v155, v154, v155, 0x3e2aaaab
	v_fma_f32 v155, v154, v155, 0.5
	v_fma_f32 v155, v154, v155, 1.0
	v_mul_f32_e32 v155, v154, v155
	v_add_f32_e32 v252, -1.0, v252
	v_cndmask_b32_e32 v155, v155, v252, vcc
	v_add_f32_e32 v154, v54, v138
	v_mul_f32_e32 v154, 0xbfb8aa3b, v154
	v_exp_f32_e32 v154, v154
	s_nop 0
	v_add_f32_e32 v154, 1.0, v154
	v_rcp_f32_e32 v154, v154
	s_nop 0
	v_mul_f32_e32 v154, v134, v154
	v_add_f32_e32 v156, v154, v154
	v_cmp_nlt_f32_e32 vcc, s4, v156
	v_mul_f32_e32 v252, 0x3fb8aa3b, v156
	v_exp_f32_e32 v252, v252
	v_fmamk_f32 v157, v156, 0x3ab60b61, v237
	v_fmaak_f32 v157, v156, v157, 0x3d2aaaab
	v_fmaak_f32 v157, v156, v157, 0x3e2aaaab
	v_fma_f32 v157, v156, v157, 0.5
	v_fma_f32 v157, v156, v157, 1.0
	v_mul_f32_e32 v158, v156, v157
	v_add_f32_e32 v252, -1.0, v252
	v_cndmask_b32_e32 v158, v158, v252, vcc
	v_add_f32_e32 v156, v55, v139
	v_mul_f32_e32 v156, 0xbfb8aa3b, v156
	v_exp_f32_e32 v156, v156
	s_nop 0
	v_add_f32_e32 v156, 1.0, v156
	v_rcp_f32_e32 v156, v156
	s_nop 0
	v_mul_f32_e32 v156, v135, v156
	v_add_f32_e32 v159, v156, v156
	v_cmp_nlt_f32_e32 vcc, s4, v159
	v_mul_f32_e32 v252, 0x3fb8aa3b, v159
	v_exp_f32_e32 v252, v252
	v_fmamk_f32 v157, v159, 0x3ab60b61, v237
	v_fmaak_f32 v157, v159, v157, 0x3d2aaaab
	v_fmaak_f32 v157, v159, v157, 0x3e2aaaab
	v_fma_f32 v157, v159, v157, 0.5
	v_fma_f32 v157, v159, v157, 1.0
	v_mul_f32_e32 v157, v159, v157
	v_add_f32_e32 v252, -1.0, v252
	v_cndmask_b32_e32 v157, v157, v252, vcc
	v_add_f32_e32 v159, v50, v130
	v_mul_f32_e32 v159, 0xbfb8aa3b, v159
	v_add_f32_e32 v161, v48, v128
	v_exp_f32_e32 v159, v159
	v_mul_f32_e32 v161, 0xbfb8aa3b, v161
	v_exp_f32_e32 v161, v161
	v_max_f32_e64 v158, -v158, -v158
	v_add_f32_e32 v159, 1.0, v159
	v_max_f32_e32 v158, 0, v158
	v_max_f32_e64 v145, -v145, -v145
	v_rcp_f32_e32 v159, v159
	v_sqrt_f32_e32 v158, v158
	v_add_f32_e32 v161, 1.0, v161
	v_max_f32_e32 v145, 0, v145
	v_rcp_f32_e32 v161, v161
	v_sqrt_f32_e32 v145, v145
	s_waitcnt vmcnt(3)
	v_lshlrev_b32_e32 v160, 16, v153
	v_mul_f32_e32 v158, v159, v158
	v_mul_f32_e32 v158, v158, v160
	v_lshlrev_b32_e32 v160, 16, v152
	v_mul_f32_e32 v145, v161, v145
	v_mul_f32_e32 v145, v145, v160
	v_add_f32_e32 v160, v49, v129
	v_mul_f32_e32 v160, 0xbfb8aa3b, v160
	v_exp_f32_e32 v160, v160
	v_max_f32_e64 v155, -v155, -v155
	v_max_f32_e32 v155, 0, v155
	v_add_f32_e32 v159, v51, v131
	v_add_f32_e32 v160, 1.0, v160
	v_rcp_f32_e32 v160, v160
	v_sqrt_f32_e32 v155, v155
	v_mul_f32_e32 v159, 0xbfb8aa3b, v159
	v_exp_f32_e32 v159, v159
	v_and_b32_e32 v152, 0xffff0000, v152
	v_mul_f32_e32 v155, v160, v155
	v_mul_f32_e32 v155, v155, v152
	v_and_b32_e32 v152, 0xffff0000, v153
	v_max_f32_e64 v153, -v157, -v157
	v_add_f32_e32 v159, 1.0, v159
	v_max_f32_e32 v153, 0, v153
	v_rcp_f32_e32 v159, v159
	v_sqrt_f32_e32 v153, v153
	s_nop 0
	v_mul_f32_e32 v153, v159, v153
	v_mul_f32_e32 v157, v153, v152
	v_cvt_pk_bf16_f32 v152, v141, v143
	v_add_f32_e32 v141, v36, v136
	v_mul_f32_e32 v141, 0xbfb8aa3b, v141
	v_exp_f32_e32 v141, v141
	v_cvt_pk_bf16_f32 v153, v154, v156
	v_cvt_pk_bf16_f32 v154, v145, v155
	v_cvt_pk_bf16_f32 v155, v158, v157
	v_add_f32_e32 v141, 1.0, v141
	v_rcp_f32_e32 v141, v141
	global_store_dwordx2 v[168:169], v[152:153], off offset:128
	global_store_dwordx2 v[170:171], v[154:155], off offset:128
	v_mul_f32_e32 v141, v132, v141
	v_add_f32_e32 v143, v141, v141
	v_cmp_nlt_f32_e32 vcc, s4, v143
	v_mul_f32_e32 v252, 0x3fb8aa3b, v143
	v_exp_f32_e32 v252, v252
	v_fmamk_f32 v145, v143, 0x3ab60b61, v237
	v_fmaak_f32 v145, v143, v145, 0x3d2aaaab
	v_fmaak_f32 v145, v143, v145, 0x3e2aaaab
	v_fma_f32 v145, v143, v145, 0.5
	v_fma_f32 v145, v143, v145, 1.0
	v_mul_f32_e32 v145, v143, v145
	v_add_f32_e32 v252, -1.0, v252
	v_cndmask_b32_e32 v145, v145, v252, vcc
	v_add_f32_e32 v143, v37, v137
	v_mul_f32_e32 v143, 0xbfb8aa3b, v143
	v_exp_f32_e32 v143, v143
	s_nop 0
	v_add_f32_e32 v143, 1.0, v143
	v_rcp_f32_e32 v143, v143
	s_nop 0
	v_mul_f32_e32 v143, v133, v143
	v_add_f32_e32 v152, v143, v143
	v_cmp_nlt_f32_e32 vcc, s4, v152
	v_mul_f32_e32 v252, 0x3fb8aa3b, v152
	v_exp_f32_e32 v252, v252
	v_fmamk_f32 v153, v152, 0x3ab60b61, v237
	v_fmaak_f32 v153, v152, v153, 0x3d2aaaab
	v_fmaak_f32 v153, v152, v153, 0x3e2aaaab
	v_fma_f32 v153, v152, v153, 0.5
	v_fma_f32 v153, v152, v153, 1.0
	v_mul_f32_e32 v153, v152, v153
	v_add_f32_e32 v252, -1.0, v252
	v_cndmask_b32_e32 v153, v153, v252, vcc
	v_add_f32_e32 v152, v38, v138
	v_mul_f32_e32 v152, 0xbfb8aa3b, v152
	v_exp_f32_e32 v152, v152
	s_nop 0
	v_add_f32_e32 v152, 1.0, v152
	v_rcp_f32_e32 v152, v152
	s_nop 0
	v_mul_f32_e32 v152, v134, v152
	v_add_f32_e32 v154, v152, v152
	v_cmp_nlt_f32_e32 vcc, s4, v154
	v_mul_f32_e32 v252, 0x3fb8aa3b, v154
; __device__ __forceinline__ unsigned cvt_pk_bf16(float lo, float hi) { const f32x2_t v = {lo, hi}; const bf16x2_t b = __builtin_convertvector(v, bf16x2_t); return __builtin_bit_cast(unsigned, b); }
; __device__ __forceinline__ float lo_bf(unsigned w) { return __uint_as_float(w << 16); }
; __device__ __forceinline__ float hi_bf(unsigned w) { return __uint_as_float(w & 0xffff0000u); }
; __device__ __forceinline__ float sigmoidf_(float x) { return __builtin_amdgcn_rcpf(1.0f + __builtin_amdgcn_exp2f(-1.4426950408889634f * x)); }
;     __device__ __forceinline__ void operator()(AccRef acc, const Unit& u, int wr, int wc, int fr, int fq) const {
;     ...
;                 for (int m = 0; m < 4; ++m) { const size_t row = (size_t)(row0 + ai * HALF + m * 16);
;                     const u32x2 xw = xwv[m];
;                     const float xv[4] = {lo_bf(xw.x), hi_bf(xw.x), lo_bf(xw.y), hi_bf(xw.y)};
;                     float la[4], uo[4];
; #pragma unroll
;                     for (int i = 0; i < 4; ++i) { const float r = sigmoidf_(acc[ai][bj][m][0][i] + vba[i]), gi = sigmoidf_(acc[ai][bj][m][1][i] + vbx[i]);
;                         const float l = cc[i] * r; la[i] = l; const float x2 = 2.0f * l;
;                         const float em1 = (x2 > -0.25f) ? x2 * (1.0f + x2 * (0.5f + x2 * (1.0f / 6.0f + x2 * (1.0f / 24.0f + x2 * (1.0f / 120.0f + x2 * (1.0f / 720.0f)))))) : (__expf(x2) - 1.0f);
;                         uo[i] = __builtin_amdgcn_sqrtf(fmaxf(-em1, 0.0f)) * gi * xv[i]; }
;                     u32x2 w0, w1; w0.x = cvt_pk_bf16(la[0], la[1]); w0.y = cvt_pk_bf16(la[2], la[3]); w1.x = cvt_pk_bf16(uo[0], uo[1]); w1.y = cvt_pk_bf16(uo[2], uo[3]);
;                     *(u32x2*)(loga + ((size_t)dir * MT + row) * 512 + ch) = w0; *(u32x2*)(uu + ((size_t)dir * MT + row) * 512 + ch) = w1; } } }
	v_exp_f32_e32 v252, v252
	v_fmamk_f32 v155, v154, 0x3ab60b61, v237
	v_fmaak_f32 v155, v154, v155, 0x3d2aaaab
	v_fmaak_f32 v155, v154, v155, 0x3e2aaaab
	v_fma_f32 v155, v154, v155, 0.5
	v_fma_f32 v155, v154, v155, 1.0
	v_mul_f32_e32 v156, v154, v155
	v_add_f32_e32 v252, -1.0, v252
	v_cndmask_b32_e32 v156, v156, v252, vcc
	v_add_f32_e32 v154, v39, v139
	v_mul_f32_e32 v154, 0xbfb8aa3b, v154
	v_exp_f32_e32 v154, v154
	s_nop 0
	v_add_f32_e32 v154, 1.0, v154
	v_rcp_f32_e32 v154, v154
	s_nop 0
	v_mul_f32_e32 v154, v135, v154
	v_add_f32_e32 v157, v154, v154
	v_cmp_nlt_f32_e32 vcc, s4, v157
	v_mul_f32_e32 v252, 0x3fb8aa3b, v157
	v_exp_f32_e32 v252, v252
	v_fmamk_f32 v155, v157, 0x3ab60b61, v237
	v_fmaak_f32 v155, v157, v155, 0x3d2aaaab
	v_fmaak_f32 v155, v157, v155, 0x3e2aaaab
	v_fma_f32 v155, v157, v155, 0.5
	v_fma_f32 v155, v157, v155, 1.0
	v_mul_f32_e32 v155, v157, v155
	v_add_f32_e32 v252, -1.0, v252
	v_cndmask_b32_e32 v155, v155, v252, vcc
	v_add_f32_e32 v157, v34, v130
	v_mul_f32_e32 v157, 0xbfb8aa3b, v157
	v_add_f32_e32 v159, v32, v128
	v_exp_f32_e32 v157, v157
	v_mul_f32_e32 v159, 0xbfb8aa3b, v159
	v_exp_f32_e32 v159, v159
	v_max_f32_e64 v156, -v156, -v156
	v_add_f32_e32 v157, 1.0, v157
	v_max_f32_e32 v156, 0, v156
	v_max_f32_e64 v145, -v145, -v145
	v_rcp_f32_e32 v157, v157
	v_sqrt_f32_e32 v156, v156
	v_add_f32_e32 v159, 1.0, v159
	v_max_f32_e32 v145, 0, v145
	v_rcp_f32_e32 v159, v159
	v_sqrt_f32_e32 v145, v145
	s_waitcnt vmcnt(4)
	v_lshlrev_b32_e32 v158, 16, v151
	v_mul_f32_e32 v156, v157, v156
	v_mul_f32_e32 v156, v156, v158
	v_lshlrev_b32_e32 v158, 16, v150
	v_mul_f32_e32 v145, v159, v145
	v_mul_f32_e32 v145, v145, v158
	v_add_f32_e32 v158, v33, v129
	v_mul_f32_e32 v158, 0xbfb8aa3b, v158
	v_exp_f32_e32 v158, v158
	v_max_f32_e64 v153, -v153, -v153
	v_max_f32_e32 v153, 0, v153
	v_add_f32_e32 v157, v35, v131
	v_add_f32_e32 v158, 1.0, v158
	v_rcp_f32_e32 v158, v158
	v_sqrt_f32_e32 v153, v153
	v_mul_f32_e32 v157, 0xbfb8aa3b, v157
	v_exp_f32_e32 v157, v157
	v_and_b32_e32 v150, 0xffff0000, v150
	v_mul_f32_e32 v153, v158, v153
	v_mul_f32_e32 v153, v153, v150
	v_and_b32_e32 v150, 0xffff0000, v151
	v_max_f32_e64 v151, -v155, -v155
	v_add_f32_e32 v157, 1.0, v157
	v_max_f32_e32 v151, 0, v151
	v_rcp_f32_e32 v157, v157
	v_sqrt_f32_e32 v151, v151
	s_nop 0
	v_mul_f32_e32 v151, v157, v151
	v_mul_f32_e32 v155, v151, v150
	v_cvt_pk_bf16_f32 v150, v141, v143
	v_add_f32_e32 v141, v20, v136
	v_mul_f32_e32 v141, 0xbfb8aa3b, v141
	v_exp_f32_e32 v141, v141
	v_cvt_pk_bf16_f32 v151, v152, v154
	v_cvt_pk_bf16_f32 v152, v145, v153
	v_cvt_pk_bf16_f32 v153, v156, v155
	v_add_f32_e32 v141, 1.0, v141
	v_rcp_f32_e32 v141, v141
	global_store_dwordx2 v[172:173], v[150:151], off offset:128
	global_store_dwordx2 v[174:175], v[152:153], off offset:128
	v_mul_f32_e32 v141, v132, v141
	v_add_f32_e32 v143, v141, v141
	v_cmp_nlt_f32_e32 vcc, s4, v143
	v_mul_f32_e32 v252, 0x3fb8aa3b, v143
	v_exp_f32_e32 v252, v252
	v_fmamk_f32 v145, v143, 0x3ab60b61, v237
	v_fmaak_f32 v145, v143, v145, 0x3d2aaaab
	v_fmaak_f32 v145, v143, v145, 0x3e2aaaab
	v_fma_f32 v145, v143, v145, 0.5
	v_fma_f32 v145, v143, v145, 1.0
	v_mul_f32_e32 v145, v143, v145
	v_add_f32_e32 v252, -1.0, v252
	v_cndmask_b32_e32 v145, v145, v252, vcc
	v_add_f32_e32 v143, v21, v137
	v_mul_f32_e32 v143, 0xbfb8aa3b, v143
	v_exp_f32_e32 v143, v143
	s_nop 0
	v_add_f32_e32 v143, 1.0, v143
	v_rcp_f32_e32 v143, v143
	s_nop 0
	v_mul_f32_e32 v143, v133, v143
	v_add_f32_e32 v150, v143, v143
	v_cmp_nlt_f32_e32 vcc, s4, v150
	v_mul_f32_e32 v252, 0x3fb8aa3b, v150
	v_exp_f32_e32 v252, v252
	v_fmamk_f32 v151, v150, 0x3ab60b61, v237
	v_fmaak_f32 v151, v150, v151, 0x3d2aaaab
	v_fmaak_f32 v151, v150, v151, 0x3e2aaaab
	v_fma_f32 v151, v150, v151, 0.5
	v_fma_f32 v151, v150, v151, 1.0
	v_mul_f32_e32 v151, v150, v151
	v_add_f32_e32 v252, -1.0, v252
	v_cndmask_b32_e32 v151, v151, v252, vcc
	v_add_f32_e32 v150, v22, v138
	v_mul_f32_e32 v150, 0xbfb8aa3b, v150
	v_exp_f32_e32 v150, v150
	s_nop 0
	v_add_f32_e32 v150, 1.0, v150
	v_rcp_f32_e32 v150, v150
	s_nop 0
	v_mul_f32_e32 v150, v134, v150
	v_add_f32_e32 v152, v150, v150
	v_cmp_nlt_f32_e32 vcc, s4, v152
	v_mul_f32_e32 v252, 0x3fb8aa3b, v152
	v_exp_f32_e32 v252, v252
	v_fmamk_f32 v153, v152, 0x3ab60b61, v237
	v_fmaak_f32 v153, v152, v153, 0x3d2aaaab
	v_fmaak_f32 v153, v152, v153, 0x3e2aaaab
	v_fma_f32 v153, v152, v153, 0.5
	v_fma_f32 v153, v152, v153, 1.0
	v_mul_f32_e32 v154, v152, v153
	v_add_f32_e32 v252, -1.0, v252
	v_cndmask_b32_e32 v154, v154, v252, vcc
	v_add_f32_e32 v152, v23, v139
	v_mul_f32_e32 v152, 0xbfb8aa3b, v152
	v_exp_f32_e32 v152, v152
	s_nop 0
	v_add_f32_e32 v152, 1.0, v152
	v_rcp_f32_e32 v152, v152
	s_nop 0
	v_mul_f32_e32 v152, v135, v152
	v_add_f32_e32 v155, v152, v152
	v_cmp_nlt_f32_e32 vcc, s4, v155
	v_mul_f32_e32 v252, 0x3fb8aa3b, v155
	v_exp_f32_e32 v252, v252
	v_fmamk_f32 v153, v155, 0x3ab60b61, v237
	v_fmaak_f32 v153, v155, v153, 0x3d2aaaab
	v_fmaak_f32 v153, v155, v153, 0x3e2aaaab
	v_fma_f32 v153, v155, v153, 0.5
	v_fma_f32 v153, v155, v153, 1.0
	v_mul_f32_e32 v153, v155, v153
	v_add_f32_e32 v252, -1.0, v252
	v_cndmask_b32_e32 v153, v153, v252, vcc
	v_add_f32_e32 v155, v18, v130
	v_mul_f32_e32 v155, 0xbfb8aa3b, v155
	v_add_f32_e32 v157, v16, v128
	v_exp_f32_e32 v155, v155
	v_mul_f32_e32 v157, 0xbfb8aa3b, v157
	v_exp_f32_e32 v157, v157
	v_max_f32_e64 v154, -v154, -v154
	v_add_f32_e32 v155, 1.0, v155
	v_max_f32_e32 v154, 0, v154
	v_max_f32_e64 v145, -v145, -v145
	v_rcp_f32_e32 v155, v155
	v_sqrt_f32_e32 v154, v154
	v_add_f32_e32 v157, 1.0, v157
	v_max_f32_e32 v145, 0, v145
	v_rcp_f32_e32 v157, v157
	v_sqrt_f32_e32 v145, v145
	s_waitcnt vmcnt(5)
; __device__ __forceinline__ unsigned cvt_pk_bf16(float lo, float hi) { const f32x2_t v = {lo, hi}; const bf16x2_t b = __builtin_convertvector(v, bf16x2_t); return __builtin_bit_cast(unsigned, b); }
; __device__ __forceinline__ float lo_bf(unsigned w) { return __uint_as_float(w << 16); }
; __device__ __forceinline__ float hi_bf(unsigned w) { return __uint_as_float(w & 0xffff0000u); }
; __device__ __forceinline__ float sigmoidf_(float x) { return __builtin_amdgcn_rcpf(1.0f + __builtin_amdgcn_exp2f(-1.4426950408889634f * x)); }
;     __device__ __forceinline__ void operator()(AccRef acc, const Unit& u, int wr, int wc, int fr, int fq) const {
;     ...
;                 for (int m = 0; m < 4; ++m) { const size_t row = (size_t)(row0 + ai * HALF + m * 16);
;                     const u32x2 xw = xwv[m];
;                     const float xv[4] = {lo_bf(xw.x), hi_bf(xw.x), lo_bf(xw.y), hi_bf(xw.y)};
;                     float la[4], uo[4];
; #pragma unroll
;                     for (int i = 0; i < 4; ++i) { const float r = sigmoidf_(acc[ai][bj][m][0][i] + vba[i]), gi = sigmoidf_(acc[ai][bj][m][1][i] + vbx[i]);
;                         const float l = cc[i] * r; la[i] = l; const float x2 = 2.0f * l;
;                         const float em1 = (x2 > -0.25f) ? x2 * (1.0f + x2 * (0.5f + x2 * (1.0f / 6.0f + x2 * (1.0f / 24.0f + x2 * (1.0f / 120.0f + x2 * (1.0f / 720.0f)))))) : (__expf(x2) - 1.0f);
;                         uo[i] = __builtin_amdgcn_sqrtf(fmaxf(-em1, 0.0f)) * gi * xv[i]; }
;                     u32x2 w0, w1; w0.x = cvt_pk_bf16(la[0], la[1]); w0.y = cvt_pk_bf16(la[2], la[3]); w1.x = cvt_pk_bf16(uo[0], uo[1]); w1.y = cvt_pk_bf16(uo[2], uo[3]);
;                     *(u32x2*)(loga + ((size_t)dir * MT + row) * 512 + ch) = w0; *(u32x2*)(uu + ((size_t)dir * MT + row) * 512 + ch) = w1; } } }
	v_lshlrev_b32_e32 v156, 16, v149
	v_mul_f32_e32 v154, v155, v154
	v_mul_f32_e32 v154, v154, v156
	v_lshlrev_b32_e32 v156, 16, v148
	v_mul_f32_e32 v145, v157, v145
	v_mul_f32_e32 v145, v145, v156
	v_add_f32_e32 v156, v17, v129
	v_mul_f32_e32 v156, 0xbfb8aa3b, v156
	v_exp_f32_e32 v156, v156
	v_max_f32_e64 v151, -v151, -v151
	v_max_f32_e32 v151, 0, v151
	v_add_f32_e32 v155, v19, v131
	v_add_f32_e32 v156, 1.0, v156
	v_rcp_f32_e32 v156, v156
	v_sqrt_f32_e32 v151, v151
	v_add_f32_e32 v136, v4, v136
	v_mul_f32_e32 v155, 0xbfb8aa3b, v155
	v_mul_f32_e32 v136, 0xbfb8aa3b, v136
	v_exp_f32_e32 v155, v155
	v_exp_f32_e32 v136, v136
	v_and_b32_e32 v148, 0xffff0000, v148
	v_mul_f32_e32 v151, v156, v151
	v_mul_f32_e32 v151, v151, v148
	v_and_b32_e32 v148, 0xffff0000, v149
	v_max_f32_e64 v149, -v153, -v153
	v_add_f32_e32 v155, 1.0, v155
	v_max_f32_e32 v149, 0, v149
	v_add_f32_e32 v136, 1.0, v136
	v_rcp_f32_e32 v155, v155
	v_sqrt_f32_e32 v149, v149
	v_rcp_f32_e32 v136, v136
	v_mul_f32_e32 v149, v155, v149
	v_mul_f32_e32 v132, v132, v136
	v_mul_f32_e32 v153, v149, v148
	v_cvt_pk_bf16_f32 v148, v141, v143
	v_add_f32_e32 v141, v132, v132
	v_cvt_pk_bf16_f32 v149, v150, v152
	v_cvt_pk_bf16_f32 v150, v145, v151
	v_cvt_pk_bf16_f32 v151, v154, v153
	global_store_dwordx2 v[176:177], v[148:149], off offset:128
	global_store_dwordx2 v[178:179], v[150:151], off offset:128
	v_cmp_nlt_f32_e32 vcc, s4, v141
	v_mul_f32_e32 v252, 0x3fb8aa3b, v141
	v_exp_f32_e32 v252, v252
	v_fmamk_f32 v136, v141, 0x3ab60b61, v237
	v_fmaak_f32 v136, v141, v136, 0x3d2aaaab
	v_fmaak_f32 v136, v141, v136, 0x3e2aaaab
	v_fma_f32 v136, v141, v136, 0.5
	v_fma_f32 v136, v141, v136, 1.0
	v_mul_f32_e32 v136, v141, v136
	v_add_f32_e32 v252, -1.0, v252
	v_cndmask_b32_e32 v136, v136, v252, vcc
	v_add_f32_e32 v137, v5, v137
	v_mul_f32_e32 v137, 0xbfb8aa3b, v137
	v_exp_f32_e32 v137, v137
	s_nop 0
	v_add_f32_e32 v137, 1.0, v137
	v_rcp_f32_e32 v137, v137
	s_nop 0
	v_mul_f32_e32 v133, v133, v137
	v_add_f32_e32 v141, v133, v133
	v_cmp_nlt_f32_e32 vcc, s4, v141
	v_mul_f32_e32 v252, 0x3fb8aa3b, v141
	v_exp_f32_e32 v252, v252
	v_fmamk_f32 v137, v141, 0x3ab60b61, v237
	v_fmaak_f32 v137, v141, v137, 0x3d2aaaab
	v_fmaak_f32 v137, v141, v137, 0x3e2aaaab
	v_fma_f32 v137, v141, v137, 0.5
	v_fma_f32 v137, v141, v137, 1.0
	v_mul_f32_e32 v137, v141, v137
	v_add_f32_e32 v252, -1.0, v252
	v_cndmask_b32_e32 v137, v137, v252, vcc
	v_add_f32_e32 v138, v6, v138
	v_mul_f32_e32 v138, 0xbfb8aa3b, v138
	v_exp_f32_e32 v138, v138
	s_nop 0
	v_add_f32_e32 v138, 1.0, v138
	v_rcp_f32_e32 v138, v138
	s_nop 0
	v_mul_f32_e32 v134, v134, v138
	v_add_f32_e32 v141, v134, v134
	v_cmp_nlt_f32_e32 vcc, s4, v141
	v_mul_f32_e32 v252, 0x3fb8aa3b, v141
	v_exp_f32_e32 v252, v252
	v_fmamk_f32 v138, v141, 0x3ab60b61, v237
	v_fmaak_f32 v138, v141, v138, 0x3d2aaaab
	v_fmaak_f32 v138, v141, v138, 0x3e2aaaab
	v_fma_f32 v138, v141, v138, 0.5
	v_fma_f32 v138, v141, v138, 1.0
	v_mul_f32_e32 v138, v141, v138
	v_add_f32_e32 v252, -1.0, v252
	v_cndmask_b32_e32 v138, v138, v252, vcc
	v_add_f32_e32 v139, v7, v139
	v_mul_f32_e32 v139, 0xbfb8aa3b, v139
	v_exp_f32_e32 v139, v139
	s_nop 0
	v_add_f32_e32 v139, 1.0, v139
	v_rcp_f32_e32 v139, v139
	s_nop 0
	v_mul_f32_e32 v135, v135, v139
	v_add_f32_e32 v141, v135, v135
	v_cmp_nlt_f32_e32 vcc, s4, v141
	v_mul_f32_e32 v252, 0x3fb8aa3b, v141
	v_exp_f32_e32 v252, v252
	v_fmamk_f32 v139, v141, 0x3ab60b61, v237
	v_fmaak_f32 v139, v141, v139, 0x3d2aaaab
	v_fmaak_f32 v139, v141, v139, 0x3e2aaaab
	v_fma_f32 v139, v141, v139, 0.5
	v_fma_f32 v139, v141, v139, 1.0
	v_mul_f32_e32 v139, v141, v139
	v_add_f32_e32 v252, -1.0, v252
	v_cndmask_b32_e32 v139, v139, v252, vcc
	v_add_f32_e32 v128, v0, v128
	v_add_f32_e32 v129, v1, v129
	v_add_f32_e32 v131, v3, v131
	v_mul_f32_e32 v128, 0xbfb8aa3b, v128
	v_mul_f32_e32 v129, 0xbfb8aa3b, v129
	v_add_f32_e32 v130, v2, v130
	v_mul_f32_e32 v131, 0xbfb8aa3b, v131
	v_exp_f32_e32 v128, v128
	v_exp_f32_e32 v129, v129
	v_mul_f32_e32 v130, 0xbfb8aa3b, v130
	v_exp_f32_e32 v131, v131
	v_exp_f32_e32 v130, v130
	v_max_f32_e64 v136, -v136, -v136
	v_max_f32_e64 v137, -v137, -v137
	v_add_f32_e32 v128, 1.0, v128
	v_max_f32_e32 v136, 0, v136
	v_add_f32_e32 v129, 1.0, v129
	v_max_f32_e32 v137, 0, v137
	v_max_f32_e64 v138, -v138, -v138
	v_max_f32_e64 v139, -v139, -v139
	v_add_f32_e32 v131, 1.0, v131
	v_rcp_f32_e32 v128, v128
	v_sqrt_f32_e32 v136, v136
	v_rcp_f32_e32 v129, v129
	v_sqrt_f32_e32 v137, v137
	v_add_f32_e32 v130, 1.0, v130
	v_max_f32_e32 v138, 0, v138
	v_max_f32_e32 v139, 0, v139
	v_rcp_f32_e32 v131, v131
	v_rcp_f32_e32 v130, v130
	v_sqrt_f32_e32 v138, v138
	v_sqrt_f32_e32 v139, v139
	v_pk_mul_f32 v[128:129], v[128:129], v[136:137]
	s_waitcnt vmcnt(6)
	v_lshlrev_b32_e32 v136, 16, v146
	v_and_b32_e32 v137, 0xffff0000, v146
	v_pk_mul_f32 v[128:129], v[128:129], v[136:137]
	v_lshlrev_b32_e32 v136, 16, v147
	v_and_b32_e32 v137, 0xffff0000, v147
	v_pk_mul_f32 v[130:131], v[130:131], v[138:139]
	v_cvt_pk_bf16_f32 v132, v132, v133
	v_pk_mul_f32 v[130:131], v[130:131], v[136:137]
	v_cvt_pk_bf16_f32 v133, v134, v135
	s_mov_b64 s[6:7], 0
	v_cvt_pk_bf16_f32 v128, v128, v129
	v_cvt_pk_bf16_f32 v129, v130, v131
	global_store_dwordx2 v[180:181], v[132:133], off offset:128
	global_store_dwordx2 v[220:221], v[128:129], off offset:128
